# v5 plus residual-add GEMM epilogue (out-proj, down) rewritten: batched residual loads, per-half batched cross-lane reduce and atomics
# baseline (speedup 1.0000x reference)
; __device__ __forceinline__ u32x4 pack8(const f32x4 v0, const f32x4 v1) { u32x4 w; w.x = cvt_pk_bf16(v0[0], v0[1]); w.y = cvt_pk_bf16(v0[2], v0[3]); w.z = cvt_pk_bf16(v1[0], v1[1]); w.w = cvt_pk_bf16(v1[2], v1[3]); return w; }
; __device__ __forceinline__ float sq4(const f32x4 v) { return (v[0] * v[0] + v[1] * v[1]) + (v[2] * v[2] + v[3] * v[3]); }
; __device__ __forceinline__ float sum_fq(float v) { v += __shfl_xor(v, 16); v += __shfl_xor(v, 32); return v; }
;     __device__ __forceinline__ void operator()(const f32x4 (&acc)[2][2][4][2], const Unit& u, int wr, int wc, int fr, int fq) const {
;         const int row0 = u.pm * BM + wr * 64 + fr, col0 = u.pn * BM + wc * 32 + 8 * fq;
; #pragma unroll
;         for (int ai = 0; ai < 2; ++ai) {
;             u32x4 res[4][2];
; #pragma unroll
;             for (int m = 0; m < 4; ++m)
; #pragma unroll
;                 for (int bj = 0; bj < 2; ++bj) res[m][bj] = *(const u32x4*)(xb + (size_t)(row0 + ai * HALF + m * 16) * ldc + col0 + bj * HALF);
;             __builtin_amdgcn_sched_barrier(0);
; #pragma unroll
;             for (int m = 0; m < 4; ++m) {
;                 const int row = row0 + ai * HALF + m * 16; float s = 0.f;
; #pragma unroll
;                 for (int bj = 0; bj < 2; ++bj) {
;                     const size_t p = (size_t)row * ldc + col0 + bj * HALF; const u32x4 rw = res[m][bj];
;                     const f32x4 r0 = (f32x4){__builtin_bit_cast(float, rw.x << 16), __builtin_bit_cast(float, rw.x & 0xffff0000u), __builtin_bit_cast(float, rw.y << 16), __builtin_bit_cast(float, rw.y & 0xffff0000u)};
;                     const f32x4 r1 = (f32x4){__builtin_bit_cast(float, rw.z << 16), __builtin_bit_cast(float, rw.z & 0xffff0000u), __builtin_bit_cast(float, rw.w << 16), __builtin_bit_cast(float, rw.w & 0xffff0000u)};
;                     const f32x4 v0 = acc[ai][bj][m][0] + r0, v1 = acc[ai][bj][m][1] + r1;
;                     if (xout) { *(f32x4*)(xout + p) = v0; *(f32x4*)(xout + p + 4) = v1; }
;                     else { *(u32x4*)(xb + p) = pack8(v0, v1); s += sq4(v0) + sq4(v1); }
;                 }
;                 if (!xout) { s = sum_fq(s); if (fq == 0) atomicAdd(ssnext + row, s); }
.LBB0_62:
	v_readlane_b32 s76, v251, 32
	s_and_b64 vcc, exec, s[16:17]
	s_cbranch_vccnz .Lresid_xout
	s_waitcnt vmcnt(14)
	v_lshlrev_b32_e32 v246, 16, v120
	v_lshlrev_b32_e32 v247, 16, v121
	v_lshlrev_b32_e32 v248, 16, v122
	v_lshlrev_b32_e32 v249, 16, v123
	v_and_b32_e32 v120, 0xffff0000, v120
	v_and_b32_e32 v121, 0xffff0000, v121
	v_and_b32_e32 v122, 0xffff0000, v122
	v_and_b32_e32 v123, 0xffff0000, v123
	v_add_f32_e32 v128, v128, v246
	v_add_f32_e32 v129, v129, v120
	v_add_f32_e32 v130, v130, v247
	v_add_f32_e32 v131, v131, v121
	v_add_f32_e32 v124, v124, v248
	v_add_f32_e32 v125, v125, v122
	v_add_f32_e32 v126, v126, v249
	v_add_f32_e32 v127, v127, v123
	v_cvt_pk_bf16_f32 v120, v128, v129
	v_cvt_pk_bf16_f32 v121, v130, v131
	v_cvt_pk_bf16_f32 v122, v124, v125
	v_cvt_pk_bf16_f32 v123, v126, v127
	global_store_dwordx4 v238, v[120:123], s[20:21]
	v_lshlrev_b32_e32 v246, 16, v132
	v_lshlrev_b32_e32 v247, 16, v133
	v_lshlrev_b32_e32 v248, 16, v134
	v_lshlrev_b32_e32 v249, 16, v135
	v_and_b32_e32 v132, 0xffff0000, v132
	v_and_b32_e32 v133, 0xffff0000, v133
	v_and_b32_e32 v134, 0xffff0000, v134
	v_and_b32_e32 v135, 0xffff0000, v135
	v_add_f32_e32 v116, v116, v246
	v_add_f32_e32 v117, v117, v132
	v_add_f32_e32 v118, v118, v247
	v_add_f32_e32 v119, v119, v133
	v_add_f32_e32 v112, v112, v248
	v_add_f32_e32 v113, v113, v134
	v_add_f32_e32 v114, v114, v249
	v_add_f32_e32 v115, v115, v135
	v_cvt_pk_bf16_f32 v132, v116, v117
	v_cvt_pk_bf16_f32 v133, v118, v119
	v_cvt_pk_bf16_f32 v134, v112, v113
	v_cvt_pk_bf16_f32 v135, v114, v115
	global_store_dwordx4 v238, v[132:135], s[20:21] offset:256
	v_mul_f32_e32 v128, v128, v128
	v_fmac_f32_e32 v128, v129, v129
	v_fmac_f32_e32 v128, v130, v130
	v_fmac_f32_e32 v128, v131, v131
	v_fmac_f32_e32 v128, v124, v124
	v_fmac_f32_e32 v128, v125, v125
	v_fmac_f32_e32 v128, v126, v126
	v_fmac_f32_e32 v128, v127, v127
	v_fmac_f32_e32 v128, v116, v116
	v_fmac_f32_e32 v128, v117, v117
	v_fmac_f32_e32 v128, v118, v118
	v_fmac_f32_e32 v128, v119, v119
	v_fmac_f32_e32 v128, v112, v112
	v_fmac_f32_e32 v128, v113, v113
	v_fmac_f32_e32 v128, v114, v114
	v_fmac_f32_e32 v128, v115, v115
	s_waitcnt vmcnt(14)
	v_lshlrev_b32_e32 v246, 16, v136
	v_lshlrev_b32_e32 v247, 16, v137
	v_lshlrev_b32_e32 v248, 16, v138
	v_lshlrev_b32_e32 v249, 16, v139
	v_and_b32_e32 v136, 0xffff0000, v136
	v_and_b32_e32 v137, 0xffff0000, v137
	v_and_b32_e32 v138, 0xffff0000, v138
	v_and_b32_e32 v139, 0xffff0000, v139
	v_add_f32_e32 v108, v108, v246
	v_add_f32_e32 v109, v109, v136
	v_add_f32_e32 v110, v110, v247
	v_add_f32_e32 v111, v111, v137
	v_add_f32_e32 v104, v104, v248
	v_add_f32_e32 v105, v105, v138
	v_add_f32_e32 v106, v106, v249
	v_add_f32_e32 v107, v107, v139
	v_cvt_pk_bf16_f32 v136, v108, v109
	v_cvt_pk_bf16_f32 v137, v110, v111
	v_cvt_pk_bf16_f32 v138, v104, v105
	v_cvt_pk_bf16_f32 v139, v106, v107
	global_store_dwordx4 v239, v[136:139], s[20:21]
	v_lshlrev_b32_e32 v246, 16, v140
	v_lshlrev_b32_e32 v247, 16, v141
	v_lshlrev_b32_e32 v248, 16, v142
	v_lshlrev_b32_e32 v249, 16, v143
	v_and_b32_e32 v140, 0xffff0000, v140
	v_and_b32_e32 v141, 0xffff0000, v141
	v_and_b32_e32 v142, 0xffff0000, v142
	v_and_b32_e32 v143, 0xffff0000, v143
	v_add_f32_e32 v100, v100, v246
	v_add_f32_e32 v101, v101, v140
	v_add_f32_e32 v102, v102, v247
	v_add_f32_e32 v103, v103, v141
	v_add_f32_e32 v96, v96, v248
	v_add_f32_e32 v97, v97, v142
	v_add_f32_e32 v98, v98, v249
	v_add_f32_e32 v99, v99, v143
	v_cvt_pk_bf16_f32 v140, v100, v101
	v_cvt_pk_bf16_f32 v141, v102, v103
	v_cvt_pk_bf16_f32 v142, v96, v97
	v_cvt_pk_bf16_f32 v143, v98, v99
	global_store_dwordx4 v239, v[140:143], s[20:21] offset:256
	v_mul_f32_e32 v108, v108, v108
	v_fmac_f32_e32 v108, v109, v109
	v_fmac_f32_e32 v108, v110, v110
	v_fmac_f32_e32 v108, v111, v111
	v_fmac_f32_e32 v108, v104, v104
	v_fmac_f32_e32 v108, v105, v105
	v_fmac_f32_e32 v108, v106, v106
	v_fmac_f32_e32 v108, v107, v107
	v_fmac_f32_e32 v108, v100, v100
	v_fmac_f32_e32 v108, v101, v101
	v_fmac_f32_e32 v108, v102, v102
	v_fmac_f32_e32 v108, v103, v103
	v_fmac_f32_e32 v108, v96, v96
	v_fmac_f32_e32 v108, v97, v97
	v_fmac_f32_e32 v108, v98, v98
	v_fmac_f32_e32 v108, v99, v99
	s_waitcnt vmcnt(14)
	v_lshlrev_b32_e32 v246, 16, v144
	v_lshlrev_b32_e32 v247, 16, v145
	v_lshlrev_b32_e32 v248, 16, v146
	v_lshlrev_b32_e32 v249, 16, v147
	v_and_b32_e32 v144, 0xffff0000, v144
	v_and_b32_e32 v145, 0xffff0000, v145
	v_and_b32_e32 v146, 0xffff0000, v146
	v_and_b32_e32 v147, 0xffff0000, v147
	v_add_f32_e32 v92, v92, v246
	v_add_f32_e32 v93, v93, v144
	v_add_f32_e32 v94, v94, v247
	v_add_f32_e32 v95, v95, v145
	v_add_f32_e32 v88, v88, v248
	v_add_f32_e32 v89, v89, v146
	v_add_f32_e32 v90, v90, v249
	v_add_f32_e32 v91, v91, v147
	v_cvt_pk_bf16_f32 v144, v92, v93
	v_cvt_pk_bf16_f32 v145, v94, v95
	v_cvt_pk_bf16_f32 v146, v88, v89
	v_cvt_pk_bf16_f32 v147, v90, v91
	global_store_dwordx4 v240, v[144:147], s[20:21]
	v_lshlrev_b32_e32 v246, 16, v148
	v_lshlrev_b32_e32 v247, 16, v149
	v_lshlrev_b32_e32 v248, 16, v150
	v_lshlrev_b32_e32 v249, 16, v151
	v_and_b32_e32 v148, 0xffff0000, v148
	v_and_b32_e32 v149, 0xffff0000, v149
	v_and_b32_e32 v150, 0xffff0000, v150
	v_and_b32_e32 v151, 0xffff0000, v151
	v_add_f32_e32 v84, v84, v246
	v_add_f32_e32 v85, v85, v148
	v_add_f32_e32 v86, v86, v247
	v_add_f32_e32 v87, v87, v149
	v_add_f32_e32 v80, v80, v248
	v_add_f32_e32 v81, v81, v150
	v_add_f32_e32 v82, v82, v249
	v_add_f32_e32 v83, v83, v151
	v_cvt_pk_bf16_f32 v148, v84, v85
	v_cvt_pk_bf16_f32 v149, v86, v87
	v_cvt_pk_bf16_f32 v150, v80, v81
	v_cvt_pk_bf16_f32 v151, v82, v83
	global_store_dwordx4 v240, v[148:151], s[20:21] offset:256
	v_mul_f32_e32 v92, v92, v92
	v_fmac_f32_e32 v92, v93, v93
	v_fmac_f32_e32 v92, v94, v94
	v_fmac_f32_e32 v92, v95, v95
	v_fmac_f32_e32 v92, v88, v88
	v_fmac_f32_e32 v92, v89, v89
	v_fmac_f32_e32 v92, v90, v90
	v_fmac_f32_e32 v92, v91, v91
	v_fmac_f32_e32 v92, v84, v84
	v_fmac_f32_e32 v92, v85, v85
	v_fmac_f32_e32 v92, v86, v86
	v_fmac_f32_e32 v92, v87, v87
	v_fmac_f32_e32 v92, v80, v80
	v_fmac_f32_e32 v92, v81, v81
	v_fmac_f32_e32 v92, v82, v82
	v_fmac_f32_e32 v92, v83, v83
	s_waitcnt vmcnt(14)
; __device__ __forceinline__ u32x4 pack8(const f32x4 v0, const f32x4 v1) { u32x4 w; w.x = cvt_pk_bf16(v0[0], v0[1]); w.y = cvt_pk_bf16(v0[2], v0[3]); w.z = cvt_pk_bf16(v1[0], v1[1]); w.w = cvt_pk_bf16(v1[2], v1[3]); return w; }
; __device__ __forceinline__ float sq4(const f32x4 v) { return (v[0] * v[0] + v[1] * v[1]) + (v[2] * v[2] + v[3] * v[3]); }
; __device__ __forceinline__ float sum_fq(float v) { v += __shfl_xor(v, 16); v += __shfl_xor(v, 32); return v; }
;     __device__ __forceinline__ void operator()(const f32x4 (&acc)[2][2][4][2], const Unit& u, int wr, int wc, int fr, int fq) const {
;     ...
;             for (int m = 0; m < 4; ++m) {
;                 const int row = row0 + ai * HALF + m * 16; float s = 0.f;
; #pragma unroll
;                 for (int bj = 0; bj < 2; ++bj) {
;                     const size_t p = (size_t)row * ldc + col0 + bj * HALF; const u32x4 rw = res[m][bj];
;                     const f32x4 r0 = (f32x4){__builtin_bit_cast(float, rw.x << 16), __builtin_bit_cast(float, rw.x & 0xffff0000u), __builtin_bit_cast(float, rw.y << 16), __builtin_bit_cast(float, rw.y & 0xffff0000u)};
;                     const f32x4 r1 = (f32x4){__builtin_bit_cast(float, rw.z << 16), __builtin_bit_cast(float, rw.z & 0xffff0000u), __builtin_bit_cast(float, rw.w << 16), __builtin_bit_cast(float, rw.w & 0xffff0000u)};
;                     const f32x4 v0 = acc[ai][bj][m][0] + r0, v1 = acc[ai][bj][m][1] + r1;
;                     if (xout) { *(f32x4*)(xout + p) = v0; *(f32x4*)(xout + p + 4) = v1; }
;                     else { *(u32x4*)(xb + p) = pack8(v0, v1); s += sq4(v0) + sq4(v1); }
;                 }
;                 if (!xout) { s = sum_fq(s); if (fq == 0) atomicAdd(ssnext + row, s); }
	v_lshlrev_b32_e32 v246, 16, v152
	v_lshlrev_b32_e32 v247, 16, v153
	v_lshlrev_b32_e32 v248, 16, v154
	v_lshlrev_b32_e32 v249, 16, v155
	v_and_b32_e32 v152, 0xffff0000, v152
	v_and_b32_e32 v153, 0xffff0000, v153
	v_and_b32_e32 v154, 0xffff0000, v154
	v_and_b32_e32 v155, 0xffff0000, v155
	v_add_f32_e32 v76, v76, v246
	v_add_f32_e32 v77, v77, v152
	v_add_f32_e32 v78, v78, v247
	v_add_f32_e32 v79, v79, v153
	v_add_f32_e32 v72, v72, v248
	v_add_f32_e32 v73, v73, v154
	v_add_f32_e32 v74, v74, v249
	v_add_f32_e32 v75, v75, v155
	v_cvt_pk_bf16_f32 v152, v76, v77
	v_cvt_pk_bf16_f32 v153, v78, v79
	v_cvt_pk_bf16_f32 v154, v72, v73
	v_cvt_pk_bf16_f32 v155, v74, v75
	global_store_dwordx4 v241, v[152:155], s[20:21]
	v_lshlrev_b32_e32 v246, 16, v166
	v_lshlrev_b32_e32 v247, 16, v167
	v_lshlrev_b32_e32 v248, 16, v168
	v_lshlrev_b32_e32 v249, 16, v169
	v_and_b32_e32 v166, 0xffff0000, v166
	v_and_b32_e32 v167, 0xffff0000, v167
	v_and_b32_e32 v168, 0xffff0000, v168
	v_and_b32_e32 v169, 0xffff0000, v169
	v_add_f32_e32 v68, v68, v246
	v_add_f32_e32 v69, v69, v166
	v_add_f32_e32 v70, v70, v247
	v_add_f32_e32 v71, v71, v167
	v_add_f32_e32 v64, v64, v248
	v_add_f32_e32 v65, v65, v168
	v_add_f32_e32 v66, v66, v249
	v_add_f32_e32 v67, v67, v169
	v_cvt_pk_bf16_f32 v166, v68, v69
	v_cvt_pk_bf16_f32 v167, v70, v71
	v_cvt_pk_bf16_f32 v168, v64, v65
	v_cvt_pk_bf16_f32 v169, v66, v67
	global_store_dwordx4 v241, v[166:169], s[20:21] offset:256
	v_mul_f32_e32 v76, v76, v76
	v_fmac_f32_e32 v76, v77, v77
	v_fmac_f32_e32 v76, v78, v78
	v_fmac_f32_e32 v76, v79, v79
	v_fmac_f32_e32 v76, v72, v72
	v_fmac_f32_e32 v76, v73, v73
	v_fmac_f32_e32 v76, v74, v74
	v_fmac_f32_e32 v76, v75, v75
	v_fmac_f32_e32 v76, v68, v68
	v_fmac_f32_e32 v76, v69, v69
	v_fmac_f32_e32 v76, v70, v70
	v_fmac_f32_e32 v76, v71, v71
	v_fmac_f32_e32 v76, v64, v64
	v_fmac_f32_e32 v76, v65, v65
	v_fmac_f32_e32 v76, v66, v66
	v_fmac_f32_e32 v76, v67, v67
	v_xor_b32_e32 v132, 16, v220
	v_xor_b32_e32 v133, 32, v220
	v_lshlrev_b32_e32 v132, 2, v132
	v_lshlrev_b32_e32 v133, 2, v133
	v_lshlrev_b32_e32 v134, 2, v250
	s_nop 1
	ds_bpermute_b32 v120, v132, v128
	ds_bpermute_b32 v136, v132, v108
	ds_bpermute_b32 v144, v132, v92
	ds_bpermute_b32 v152, v132, v76
	s_waitcnt lgkmcnt(0)
	v_add_f32_e32 v128, v128, v120
	v_add_f32_e32 v108, v108, v136
	v_add_f32_e32 v92, v92, v144
	v_add_f32_e32 v76, v76, v152
	ds_bpermute_b32 v120, v133, v128
	ds_bpermute_b32 v136, v133, v108
	ds_bpermute_b32 v144, v133, v92
	ds_bpermute_b32 v152, v133, v76
	s_waitcnt lgkmcnt(0)
	v_add_f32_e32 v128, v128, v120
	v_add_f32_e32 v108, v108, v136
	v_add_f32_e32 v92, v92, v144
	v_add_f32_e32 v76, v76, v152
	s_and_saveexec_b64 s[44:45], s[38:39]
	global_atomic_add_f32 v134, v128, s[6:7]
	global_atomic_add_f32 v134, v108, s[6:7] offset:64
	global_atomic_add_f32 v134, v92, s[6:7] offset:128
	global_atomic_add_f32 v134, v76, s[6:7] offset:192
	s_or_b64 exec, exec, s[44:45]
	s_waitcnt vmcnt(18)
	v_lshlrev_b32_e32 v246, 16, v170
	v_lshlrev_b32_e32 v247, 16, v171
	v_lshlrev_b32_e32 v248, 16, v172
	v_lshlrev_b32_e32 v249, 16, v173
	v_and_b32_e32 v170, 0xffff0000, v170
	v_and_b32_e32 v171, 0xffff0000, v171
	v_and_b32_e32 v172, 0xffff0000, v172
	v_and_b32_e32 v173, 0xffff0000, v173
	v_add_f32_e32 v60, v60, v246
	v_add_f32_e32 v61, v61, v170
	v_add_f32_e32 v62, v62, v247
	v_add_f32_e32 v63, v63, v171
	v_add_f32_e32 v56, v56, v248
	v_add_f32_e32 v57, v57, v172
	v_add_f32_e32 v58, v58, v249
	v_add_f32_e32 v59, v59, v173
	v_cvt_pk_bf16_f32 v170, v60, v61
	v_cvt_pk_bf16_f32 v171, v62, v63
	v_cvt_pk_bf16_f32 v172, v56, v57
	v_cvt_pk_bf16_f32 v173, v58, v59
	global_store_dwordx4 v242, v[170:173], s[20:21]
	v_lshlrev_b32_e32 v246, 16, v174
	v_lshlrev_b32_e32 v247, 16, v175
	v_lshlrev_b32_e32 v248, 16, v176
	v_lshlrev_b32_e32 v249, 16, v177
	v_and_b32_e32 v174, 0xffff0000, v174
	v_and_b32_e32 v175, 0xffff0000, v175
	v_and_b32_e32 v176, 0xffff0000, v176
	v_and_b32_e32 v177, 0xffff0000, v177
	v_add_f32_e32 v52, v52, v246
	v_add_f32_e32 v53, v53, v174
	v_add_f32_e32 v54, v54, v247
	v_add_f32_e32 v55, v55, v175
	v_add_f32_e32 v48, v48, v248
	v_add_f32_e32 v49, v49, v176
	v_add_f32_e32 v50, v50, v249
	v_add_f32_e32 v51, v51, v177
	v_cvt_pk_bf16_f32 v174, v52, v53
	v_cvt_pk_bf16_f32 v175, v54, v55
	v_cvt_pk_bf16_f32 v176, v48, v49
	v_cvt_pk_bf16_f32 v177, v50, v51
	global_store_dwordx4 v242, v[174:177], s[20:21] offset:256
	v_mul_f32_e32 v60, v60, v60
	v_fmac_f32_e32 v60, v61, v61
	v_fmac_f32_e32 v60, v62, v62
	v_fmac_f32_e32 v60, v63, v63
	v_fmac_f32_e32 v60, v56, v56
	v_fmac_f32_e32 v60, v57, v57
	v_fmac_f32_e32 v60, v58, v58
	v_fmac_f32_e32 v60, v59, v59
	v_fmac_f32_e32 v60, v52, v52
	v_fmac_f32_e32 v60, v53, v53
	v_fmac_f32_e32 v60, v54, v54
	v_fmac_f32_e32 v60, v55, v55
	v_fmac_f32_e32 v60, v48, v48
	v_fmac_f32_e32 v60, v49, v49
	v_fmac_f32_e32 v60, v50, v50
	v_fmac_f32_e32 v60, v51, v51
	s_waitcnt vmcnt(18)
; __device__ __forceinline__ u32x4 pack8(const f32x4 v0, const f32x4 v1) { u32x4 w; w.x = cvt_pk_bf16(v0[0], v0[1]); w.y = cvt_pk_bf16(v0[2], v0[3]); w.z = cvt_pk_bf16(v1[0], v1[1]); w.w = cvt_pk_bf16(v1[2], v1[3]); return w; }
; __device__ __forceinline__ float sq4(const f32x4 v) { return (v[0] * v[0] + v[1] * v[1]) + (v[2] * v[2] + v[3] * v[3]); }
; __device__ __forceinline__ float sum_fq(float v) { v += __shfl_xor(v, 16); v += __shfl_xor(v, 32); return v; }
;     __device__ __forceinline__ void operator()(const f32x4 (&acc)[2][2][4][2], const Unit& u, int wr, int wc, int fr, int fq) const {
;     ...
;             for (int m = 0; m < 4; ++m) {
;                 const int row = row0 + ai * HALF + m * 16; float s = 0.f;
; #pragma unroll
;                 for (int bj = 0; bj < 2; ++bj) {
;                     const size_t p = (size_t)row * ldc + col0 + bj * HALF; const u32x4 rw = res[m][bj];
;                     const f32x4 r0 = (f32x4){__builtin_bit_cast(float, rw.x << 16), __builtin_bit_cast(float, rw.x & 0xffff0000u), __builtin_bit_cast(float, rw.y << 16), __builtin_bit_cast(float, rw.y & 0xffff0000u)};
;                     const f32x4 r1 = (f32x4){__builtin_bit_cast(float, rw.z << 16), __builtin_bit_cast(float, rw.z & 0xffff0000u), __builtin_bit_cast(float, rw.w << 16), __builtin_bit_cast(float, rw.w & 0xffff0000u)};
;                     const f32x4 v0 = acc[ai][bj][m][0] + r0, v1 = acc[ai][bj][m][1] + r1;
;                     if (xout) { *(f32x4*)(xout + p) = v0; *(f32x4*)(xout + p + 4) = v1; }
;                     else { *(u32x4*)(xb + p) = pack8(v0, v1); s += sq4(v0) + sq4(v1); }
;                 }
;                 if (!xout) { s = sum_fq(s); if (fq == 0) atomicAdd(ssnext + row, s); }
;             }
	v_lshlrev_b32_e32 v246, 16, v178
	v_lshlrev_b32_e32 v247, 16, v179
	v_lshlrev_b32_e32 v248, 16, v180
	v_lshlrev_b32_e32 v249, 16, v181
	v_and_b32_e32 v178, 0xffff0000, v178
	v_and_b32_e32 v179, 0xffff0000, v179
	v_and_b32_e32 v180, 0xffff0000, v180
	v_and_b32_e32 v181, 0xffff0000, v181
	v_add_f32_e32 v44, v44, v246
	v_add_f32_e32 v45, v45, v178
	v_add_f32_e32 v46, v46, v247
	v_add_f32_e32 v47, v47, v179
	v_add_f32_e32 v40, v40, v248
	v_add_f32_e32 v41, v41, v180
	v_add_f32_e32 v42, v42, v249
	v_add_f32_e32 v43, v43, v181
	v_cvt_pk_bf16_f32 v178, v44, v45
	v_cvt_pk_bf16_f32 v179, v46, v47
	v_cvt_pk_bf16_f32 v180, v40, v41
	v_cvt_pk_bf16_f32 v181, v42, v43
	global_store_dwordx4 v243, v[178:181], s[20:21]
	v_lshlrev_b32_e32 v246, 16, v182
	v_lshlrev_b32_e32 v247, 16, v183
	v_lshlrev_b32_e32 v248, 16, v184
	v_lshlrev_b32_e32 v249, 16, v185
	v_and_b32_e32 v182, 0xffff0000, v182
	v_and_b32_e32 v183, 0xffff0000, v183
	v_and_b32_e32 v184, 0xffff0000, v184
	v_and_b32_e32 v185, 0xffff0000, v185
	v_add_f32_e32 v36, v36, v246
	v_add_f32_e32 v37, v37, v182
	v_add_f32_e32 v38, v38, v247
	v_add_f32_e32 v39, v39, v183
	v_add_f32_e32 v32, v32, v248
	v_add_f32_e32 v33, v33, v184
	v_add_f32_e32 v34, v34, v249
	v_add_f32_e32 v35, v35, v185
	v_cvt_pk_bf16_f32 v182, v36, v37
	v_cvt_pk_bf16_f32 v183, v38, v39
	v_cvt_pk_bf16_f32 v184, v32, v33
	v_cvt_pk_bf16_f32 v185, v34, v35
	global_store_dwordx4 v243, v[182:185], s[20:21] offset:256
	v_mul_f32_e32 v44, v44, v44
	v_fmac_f32_e32 v44, v45, v45
	v_fmac_f32_e32 v44, v46, v46
	v_fmac_f32_e32 v44, v47, v47
	v_fmac_f32_e32 v44, v40, v40
	v_fmac_f32_e32 v44, v41, v41
	v_fmac_f32_e32 v44, v42, v42
	v_fmac_f32_e32 v44, v43, v43
	v_fmac_f32_e32 v44, v36, v36
	v_fmac_f32_e32 v44, v37, v37
	v_fmac_f32_e32 v44, v38, v38
	v_fmac_f32_e32 v44, v39, v39
	v_fmac_f32_e32 v44, v32, v32
	v_fmac_f32_e32 v44, v33, v33
	v_fmac_f32_e32 v44, v34, v34
	v_fmac_f32_e32 v44, v35, v35
	s_waitcnt vmcnt(18)
	v_lshlrev_b32_e32 v246, 16, v186
	v_lshlrev_b32_e32 v247, 16, v187
	v_lshlrev_b32_e32 v248, 16, v188
	v_lshlrev_b32_e32 v249, 16, v189
	v_and_b32_e32 v186, 0xffff0000, v186
	v_and_b32_e32 v187, 0xffff0000, v187
	v_and_b32_e32 v188, 0xffff0000, v188
	v_and_b32_e32 v189, 0xffff0000, v189
	v_add_f32_e32 v28, v28, v246
	v_add_f32_e32 v29, v29, v186
	v_add_f32_e32 v30, v30, v247
	v_add_f32_e32 v31, v31, v187
	v_add_f32_e32 v24, v24, v248
	v_add_f32_e32 v25, v25, v188
	v_add_f32_e32 v26, v26, v249
	v_add_f32_e32 v27, v27, v189
	v_cvt_pk_bf16_f32 v186, v28, v29
	v_cvt_pk_bf16_f32 v187, v30, v31
	v_cvt_pk_bf16_f32 v188, v24, v25
	v_cvt_pk_bf16_f32 v189, v26, v27
	global_store_dwordx4 v244, v[186:189], s[20:21]
	v_lshlrev_b32_e32 v246, 16, v194
	v_lshlrev_b32_e32 v247, 16, v195
	v_lshlrev_b32_e32 v248, 16, v196
	v_lshlrev_b32_e32 v249, 16, v197
	v_and_b32_e32 v194, 0xffff0000, v194
	v_and_b32_e32 v195, 0xffff0000, v195
	v_and_b32_e32 v196, 0xffff0000, v196
	v_and_b32_e32 v197, 0xffff0000, v197
	v_add_f32_e32 v20, v20, v246
	v_add_f32_e32 v21, v21, v194
	v_add_f32_e32 v22, v22, v247
	v_add_f32_e32 v23, v23, v195
	v_add_f32_e32 v16, v16, v248
	v_add_f32_e32 v17, v17, v196
	v_add_f32_e32 v18, v18, v249
	v_add_f32_e32 v19, v19, v197
	v_cvt_pk_bf16_f32 v194, v20, v21
	v_cvt_pk_bf16_f32 v195, v22, v23
	v_cvt_pk_bf16_f32 v196, v16, v17
	v_cvt_pk_bf16_f32 v197, v18, v19
	global_store_dwordx4 v244, v[194:197], s[20:21] offset:256
	v_mul_f32_e32 v28, v28, v28
	v_fmac_f32_e32 v28, v29, v29
	v_fmac_f32_e32 v28, v30, v30
	v_fmac_f32_e32 v28, v31, v31
	v_fmac_f32_e32 v28, v24, v24
	v_fmac_f32_e32 v28, v25, v25
	v_fmac_f32_e32 v28, v26, v26
	v_fmac_f32_e32 v28, v27, v27
	v_fmac_f32_e32 v28, v20, v20
	v_fmac_f32_e32 v28, v21, v21
	v_fmac_f32_e32 v28, v22, v22
	v_fmac_f32_e32 v28, v23, v23
	v_fmac_f32_e32 v28, v16, v16
	v_fmac_f32_e32 v28, v17, v17
	v_fmac_f32_e32 v28, v18, v18
	v_fmac_f32_e32 v28, v19, v19
	s_waitcnt vmcnt(18)
	v_lshlrev_b32_e32 v246, 16, v198
	v_lshlrev_b32_e32 v247, 16, v199
	v_lshlrev_b32_e32 v248, 16, v200
	v_lshlrev_b32_e32 v249, 16, v201
	v_and_b32_e32 v198, 0xffff0000, v198
	v_and_b32_e32 v199, 0xffff0000, v199
	v_and_b32_e32 v200, 0xffff0000, v200
	v_and_b32_e32 v201, 0xffff0000, v201
	v_add_f32_e32 v12, v12, v246
	v_add_f32_e32 v13, v13, v198
	v_add_f32_e32 v14, v14, v247
	v_add_f32_e32 v15, v15, v199
	v_add_f32_e32 v8, v8, v248
	v_add_f32_e32 v9, v9, v200
	v_add_f32_e32 v10, v10, v249
	v_add_f32_e32 v11, v11, v201
	v_cvt_pk_bf16_f32 v198, v12, v13
	v_cvt_pk_bf16_f32 v199, v14, v15
	v_cvt_pk_bf16_f32 v200, v8, v9
	v_cvt_pk_bf16_f32 v201, v10, v11
	global_store_dwordx4 v245, v[198:201], s[20:21]
	v_lshlrev_b32_e32 v246, 16, v202
	v_lshlrev_b32_e32 v247, 16, v203
	v_lshlrev_b32_e32 v248, 16, v204
	v_lshlrev_b32_e32 v249, 16, v205
	v_and_b32_e32 v202, 0xffff0000, v202
	v_and_b32_e32 v203, 0xffff0000, v203
	v_and_b32_e32 v204, 0xffff0000, v204
	v_and_b32_e32 v205, 0xffff0000, v205
	v_add_f32_e32 v4, v4, v246
	v_add_f32_e32 v5, v5, v202
	v_add_f32_e32 v6, v6, v247
	v_add_f32_e32 v7, v7, v203
	v_add_f32_e32 v0, v0, v248
	v_add_f32_e32 v1, v1, v204
	v_add_f32_e32 v2, v2, v249
	v_add_f32_e32 v3, v3, v205
	v_cvt_pk_bf16_f32 v202, v4, v5
	v_cvt_pk_bf16_f32 v203, v6, v7
	v_cvt_pk_bf16_f32 v204, v0, v1
	v_cvt_pk_bf16_f32 v205, v2, v3
	global_store_dwordx4 v245, v[202:205], s[20:21] offset:256
	v_mul_f32_e32 v12, v12, v12
	v_fmac_f32_e32 v12, v13, v13
	v_fmac_f32_e32 v12, v14, v14
	v_fmac_f32_e32 v12, v15, v15
	v_fmac_f32_e32 v12, v8, v8
	v_fmac_f32_e32 v12, v9, v9
	v_fmac_f32_e32 v12, v10, v10
	v_fmac_f32_e32 v12, v11, v11
	v_fmac_f32_e32 v12, v4, v4
	v_fmac_f32_e32 v12, v5, v5
	v_fmac_f32_e32 v12, v6, v6
	v_fmac_f32_e32 v12, v7, v7
	v_fmac_f32_e32 v12, v0, v0
	v_fmac_f32_e32 v12, v1, v1
	v_fmac_f32_e32 v12, v2, v2
	v_fmac_f32_e32 v12, v3, v3
	ds_bpermute_b32 v170, v132, v60
	ds_bpermute_b32 v178, v132, v44
	ds_bpermute_b32 v186, v132, v28
	ds_bpermute_b32 v198, v132, v12
	s_waitcnt lgkmcnt(0)
	v_add_f32_e32 v60, v60, v170
	v_add_f32_e32 v44, v44, v178
	v_add_f32_e32 v28, v28, v186
	v_add_f32_e32 v12, v12, v198
	ds_bpermute_b32 v170, v133, v60
	ds_bpermute_b32 v178, v133, v44
	ds_bpermute_b32 v186, v133, v28
	ds_bpermute_b32 v198, v133, v12
	s_waitcnt lgkmcnt(0)
	v_add_f32_e32 v60, v60, v170
	v_add_f32_e32 v44, v44, v178
	v_add_f32_e32 v28, v28, v186
	v_add_f32_e32 v12, v12, v198
	s_and_saveexec_b64 s[44:45], s[38:39]
	global_atomic_add_f32 v134, v60, s[6:7] offset:512
	global_atomic_add_f32 v134, v44, s[6:7] offset:576
	global_atomic_add_f32 v134, v28, s[6:7] offset:640
	global_atomic_add_f32 v134, v12, s[6:7] offset:704
	s_or_b64 exec, exec, s[44:45]
	s_branch .LBB0_158

; __device__ __forceinline__ float sum_fq(float v) { v += __shfl_xor(v, 16); v += __shfl_xor(v, 32); return v; }
; #define LAS __attribute__((address_space(3)))
; #define SCHED_FENCE() __builtin_amdgcn_sched_barrier(0)
; #define NA_ISSUE(seq_, slot_) do { _Pragma("unroll") for (int j = 0; j < 4; ++j) st[slot_][j] = bld<u32x4>(R, co, ((seq_) < 8 ? (unsigned)WS_KB + rowb + (unsigned)((seq_) * 131072) : OFF_VT + rowb + (unsigned)(((seq_) - 8) * 131072)) + (unsigned)j * 8192u); } while (0)
; __device__ __forceinline__ void na_attn_block(LAS unsigned char* lds, rsrc_t R, int l, int bx, int G, int tid, int lane, int wave) {
;     ...
;         const int hp = u & 3, r = (u >> 2) & 127, b = u >> 9, h = 2 * hp + hsel;
;         int start = r - 4; start = start < 0 ? 0 : (start > 120 ? 120 : start);
;         const unsigned rowb = (unsigned)(((b * 128 + start) * 8 + 2 * hp) * 16384);
;         u32x4 st[3][4];
;     ...
;         u32x4 qraw[4]; float s0, s1;
;         { const unsigned q_off = OFF_PROJ + (unsigned)((b * SEQ + r * 64 + 16 * qg) * PROJ_W + h * HD) * 2u;
; #pragma unroll
;           for (int ks = 0; ks < 4; ++ks) qraw[ks] = bld<u32x4>(R, qo, q_off + 64 * ks);
;           const int hs = wave & 1, a0 = wave >> 1;
;           const unsigned sso = OFF_SS + (unsigned)(SS_H + (size_t)(l * 20 + 2 * hp + hs) * NTOK + b * SEQ + (start + a0) * 64) * 4u;
;           s0 = bld<float>(R, (unsigned)(lane * 4), sso); s1 = bld<float>(R, (unsigned)(lane * 4), sso + 4u * 64u * 4u); }
;         SCHED_FENCE();
;         NA_ISSUE(0, 0); NA_ISSUE(1, 1); NA_ISSUE(2, 2);
;         SCHED_FENCE();
;         *(LAS float*)(lds + NA_SSK + tid * 4) = __builtin_amdgcn_rsqf(s0 * (1.f / HD) + EPS); *(LAS float*)(lds + NA_SSK + (tid + 512) * 4) = __builtin_amdgcn_rsqf(s1 * (1.f / HD) + EPS);
;         bf16x8 qf[4];
;         { float qv[4][8]; float ss = 0.f;
; #pragma unroll
;           for (int ks = 0; ks < 4; ++ks)
; #pragma unroll
;               for (int j = 0; j < 4; ++j) { const unsigned w = qraw[ks][j]; qv[ks][2 * j] = __builtin_bit_cast(float, w << 16); qv[ks][2 * j + 1] = __builtin_bit_cast(float, w & 0xffff0000u); ss += qv[ks][2 * j] * qv[ks][2 * j] + qv[ks][2 * j + 1] * qv[ks][2 * j + 1]; }
;           ss = pg8::sum_fq(ss);
.LBB0_185:
	s_bfe_u32 s2, s11, 0x70002
	v_med3_u32 v250, s2, 4, v222
	s_ashr_i32 s16, s11, 9
	v_readfirstlane_b32 s15, v250
	s_add_i32 s15, s15, -4
	s_lshl_b32 s12, s16, 10
	s_lshl_b32 s13, s15, 3
	s_and_b32 s17, s10, 6
	s_add_i32 s13, s13, s12
	s_or_b32 s14, s13, s17
	s_lshl_b32 s12, s16, 13
	s_lshl_b32 s13, s2, 6
	v_readlane_b32 s3, v253, 32
	s_or_b32 s12, s13, s12
	v_readlane_b32 s13, v253, 30
	s_add_i32 s3, s17, s3
	s_or_b32 s12, s12, s13
	s_lshl_b32 s13, s3, 8
	s_mul_i32 s18, s12, 0x1800
	s_add_i32 s18, s13, s18
	s_add_i32 s18, s18, 0x14e00000
	s_or_b32 s19, s18, 64
	buffer_load_dwordx4 v[64:67], v232, s[40:43], s18 offen
	buffer_load_dwordx4 v[68:71], v232, s[40:43], s19 offen
	s_or_b32 s19, s18, 0x80
	s_or_b32 s18, s18, 0xc0
	buffer_load_dwordx4 v[84:87], v232, s[40:43], s19 offen
	buffer_load_dwordx4 v[92:95], v232, s[40:43], s18 offen
	s_add_i32 s17, s4, s17
	v_readlane_b32 s18, v253, 37
	s_add_i32 s18, s15, s18
	s_lshl_b32 s17, s17, 17
	s_lshl_b32 s16, s16, 15
	s_lshl_b32 s18, s18, 8
	s_add_i32 s16, s16, s17
	s_add_i32 s16, s16, s18
	s_add_i32 s17, s16, 0x1a0000
	s_add_i32 s16, s16, 0x1a0400
	buffer_load_dword v96, v234, s[40:43], s17 offen
	buffer_load_dword v97, v234, s[40:43], s16 offen
	s_lshl_b32 s14, s14, 14
	s_add_i32 s16, s14, 0x30e00000
	buffer_load_dwordx4 v[72:75], v208, s[40:43], s16 offen
	s_add_i32 s16, s14, 0x30e02000
	buffer_load_dwordx4 v[76:79], v208, s[40:43], s16 offen
	s_add_i32 s16, s14, 0x30e04000
	buffer_load_dwordx4 v[80:83], v208, s[40:43], s16 offen
	s_add_i32 s16, s14, 0x30e06000
	buffer_load_dwordx4 v[88:91], v208, s[40:43], s16 offen
	s_add_i32 s16, s14, 0x30e20000
	buffer_load_dwordx4 v[48:51], v208, s[40:43], s16 offen
	s_add_i32 s16, s14, 0x30e22000
	buffer_load_dwordx4 v[52:55], v208, s[40:43], s16 offen
	s_add_i32 s16, s14, 0x30e24000
	buffer_load_dwordx4 v[56:59], v208, s[40:43], s16 offen
	s_add_i32 s16, s14, 0x30e26000
	buffer_load_dwordx4 v[60:63], v208, s[40:43], s16 offen
	s_add_i32 s16, s14, 0x30e40000
	buffer_load_dwordx4 v[32:35], v208, s[40:43], s16 offen
	s_add_i32 s16, s14, 0x30e42000
	buffer_load_dwordx4 v[36:39], v208, s[40:43], s16 offen
	s_add_i32 s16, s14, 0x30e44000
	buffer_load_dwordx4 v[40:43], v208, s[40:43], s16 offen
	s_add_i32 s16, s14, 0x30e46000
	buffer_load_dwordx4 v[44:47], v208, s[40:43], s16 offen
	s_waitcnt vmcnt(0)
	v_and_b32_e32 v101, 0xffff0000, v64
	v_and_b32_e32 v103, 0xffff0000, v65
	v_lshlrev_b32_e32 v100, 16, v64
	v_mul_f32_e32 v64, v101, v101
	v_lshlrev_b32_e32 v102, 16, v65
	v_mul_f32_e32 v65, v103, v103
	v_fmac_f32_e32 v64, v100, v100
	v_fmac_f32_e32 v65, v102, v102
	v_lshlrev_b32_e32 v104, 16, v66
	v_and_b32_e32 v66, 0xffff0000, v66
	v_add_f32_e32 v64, v64, v65
	v_mul_f32_e32 v65, v66, v66
	v_fmac_f32_e32 v65, v104, v104
	v_lshlrev_b32_e32 v105, 16, v67
	v_and_b32_e32 v67, 0xffff0000, v67
	v_add_f32_e32 v64, v65, v64
	v_mul_f32_e32 v65, v67, v67
	v_fmac_f32_e32 v65, v105, v105
	v_lshlrev_b32_e32 v106, 16, v68
	v_and_b32_e32 v68, 0xffff0000, v68
	v_add_f32_e32 v64, v65, v64
	v_mul_f32_e32 v65, v68, v68
	v_fmac_f32_e32 v65, v106, v106
	v_lshlrev_b32_e32 v107, 16, v69
	v_and_b32_e32 v69, 0xffff0000, v69
	v_add_f32_e32 v64, v65, v64
	v_mul_f32_e32 v65, v69, v69
	v_fmac_f32_e32 v65, v107, v107
	v_lshlrev_b32_e32 v108, 16, v70
	v_and_b32_e32 v70, 0xffff0000, v70
	v_add_f32_e32 v64, v65, v64
	v_mul_f32_e32 v65, v70, v70
	v_fmac_f32_e32 v65, v108, v108
	v_lshlrev_b32_e32 v109, 16, v71
	v_and_b32_e32 v71, 0xffff0000, v71
	v_add_f32_e32 v64, v65, v64
	v_mul_f32_e32 v65, v71, v71
	v_fmac_f32_e32 v65, v109, v109
	v_and_b32_e32 v111, 0xffff0000, v84
	v_add_f32_e32 v64, v65, v64
	v_lshlrev_b32_e32 v110, 16, v84
	v_mul_f32_e32 v65, v111, v111
	v_fmac_f32_e32 v65, v110, v110
	v_and_b32_e32 v113, 0xffff0000, v85
	v_fmamk_f32 v96, v96, 0x3c000000, v218
	v_fmamk_f32 v97, v97, 0x3c000000, v218
	v_add_f32_e32 v64, v65, v64
	v_lshlrev_b32_e32 v112, 16, v85
	v_mul_f32_e32 v65, v113, v113
	v_rsq_f32_e32 v96, v96
	v_rsq_f32_e32 v97, v97
	v_fmac_f32_e32 v65, v112, v112
	v_and_b32_e32 v115, 0xffff0000, v86
	v_add_f32_e32 v64, v65, v64
	v_lshlrev_b32_e32 v114, 16, v86
	v_mul_f32_e32 v65, v115, v115
	v_fmac_f32_e32 v65, v114, v114
	v_and_b32_e32 v117, 0xffff0000, v87
	v_add_f32_e32 v64, v65, v64
	v_lshlrev_b32_e32 v116, 16, v87
	v_mul_f32_e32 v65, v117, v117
	ds_write2st64_b32 v246, v96, v97 offset1:8
	v_fmac_f32_e32 v65, v116, v116
	v_lshlrev_b32_e32 v97, 16, v93
	v_lshlrev_b32_e32 v96, 16, v92
	v_and_b32_e32 v93, 0xffff0000, v93
	v_and_b32_e32 v92, 0xffff0000, v92
	v_add_f32_e32 v84, v65, v64
	v_pk_mul_f32 v[64:65], v[92:93], v[92:93]
	v_lshlrev_b32_e32 v99, 16, v95
	v_pk_fma_f32 v[64:65], v[96:97], v[96:97], v[64:65]
	v_lshlrev_b32_e32 v98, 16, v94
	v_add_f32_e32 v64, v64, v84
	v_and_b32_e32 v95, 0xffff0000, v95
	v_and_b32_e32 v94, 0xffff0000, v94
	v_add_f32_e32 v84, v65, v64
	v_pk_mul_f32 v[64:65], v[94:95], v[94:95]
	v_add_u32_e32 v249, 0, v208
	v_pk_fma_f32 v[64:65], v[98:99], v[98:99], v[64:65]
	s_add_i32 s16, s14, 0x30e60000
	v_add_f32_e32 v64, v64, v84
	v_add_f32_e32 v64, v65, v64
	ds_bpermute_b32 v65, v235, v64
	s_waitcnt lgkmcnt(0)
	v_add_f32_e32 v64, v64, v65
	ds_bpermute_b32 v65, v236, v64
	s_waitcnt lgkmcnt(0)
; __device__ __forceinline__ unsigned cvt_pk_bf16(float lo, float hi) { unsigned r; asm volatile("v_cvt_pk_bf16_f32 %0, %1, %2" : "=v"(r) : "v"(lo), "v"(hi)); return r; }
; #define LAS __attribute__((address_space(3)))
; #define MFMA16(a, b, c) __builtin_amdgcn_mfma_f32_16x16x32_bf16((a), (b), (c), 0, 0, 0)
; #define SCHED_FENCE() __builtin_amdgcn_sched_barrier(0)
; #define NA_ISSUE(seq_, slot_) do { _Pragma("unroll") for (int j = 0; j < 4; ++j) st[slot_][j] = bld<u32x4>(R, co, ((seq_) < 8 ? (unsigned)WS_KB + rowb + (unsigned)((seq_) * 131072) : OFF_VT + rowb + (unsigned)(((seq_) - 8) * 131072)) + (unsigned)j * 8192u); } while (0)
; #define NA_WRITE(slot_, buf_) do { _Pragma("unroll") for (int j = 0; j < 4; ++j) *(LAS u32x4*)(lds + (buf_) * NA_BUF + j * 8192 + tid * 16) = st[slot_][j]; } while (0)
; __device__ __forceinline__ void na_attn_block(LAS unsigned char* lds, rsrc_t R, int l, int bx, int G, int tid, int lane, int wave) {
;     ...
;           for (int ks = 0; ks < 4; ++ks) { const f32x4 g0 = gq[ks][0], g1 = gq[ks][1];
;               u32x4 w; w.x = pg8::cvt_pk_bf16(qv[ks][0] * rq * g0[0], qv[ks][1] * rq * g0[1]); w.y = pg8::cvt_pk_bf16(qv[ks][2] * rq * g0[2], qv[ks][3] * rq * g0[3]);
;               w.z = pg8::cvt_pk_bf16(qv[ks][4] * rq * g1[0], qv[ks][5] * rq * g1[1]); w.w = pg8::cvt_pk_bf16(qv[ks][6] * rq * g1[2], qv[ks][7] * rq * g1[3]);
;               qf[ks] = __builtin_bit_cast(bf16x8, w); } }
;         NA_WRITE(0, 0);
;         __syncthreads();
;         f32x4 S[8][2];
; #pragma unroll
;         for (int a = 0; a < 8; ++a) {
;             NA_ISSUE(a + 3, a % 3);
;             SCHED_FENCE();
;             const int buf = (a & 1) * NA_BUF;
; #pragma unroll
;             for (int t = 0; t < 2; ++t) {
;                 f32x4 acc = (f32x4){0.f, 0.f, 0.f, 0.f};
; #pragma unroll
;                 for (int ks = 0; ks < 4; ++ks) { const bf16x8 kf = *(const LAS bf16x8*)(lds + kfb + buf + t * 4096 + ks * 512); acc = MFMA16(kf, qf[ks], acc); }
;                 const f32x4 rk = *(const LAS f32x4*)(lds + skb + a * 512 + t * 64);
;                 S[a][t] = acc * rk;
;             }
;             SCHED_FENCE();
;             NA_WRITE((a + 1) % 3, (a + 1) & 1);
;             __syncthreads();
	v_add_f32_e32 v64, v64, v65
	v_fmamk_f32 v64, v64, 0x3c000000, v218
	v_rsq_f32_e32 v118, v64
	s_nop 0
	v_mul_f32_e32 v64, v118, v100
	v_mul_f32_e32 v65, v118, v101
	v_mul_f32_e32 v64, v28, v64
	v_mul_f32_e32 v65, v29, v65
	v_cvt_pk_bf16_f32 v84, v64, v65
	v_mul_f32_e32 v64, v118, v102
	v_mul_f32_e32 v65, v118, v103
	v_mul_f32_e32 v64, v30, v64
	v_mul_f32_e32 v65, v31, v65
	v_cvt_pk_bf16_f32 v85, v64, v65
	v_mul_f32_e32 v64, v118, v104
	v_mul_f32_e32 v65, v118, v66
	v_mul_f32_e32 v64, v24, v64
	v_mul_f32_e32 v65, v25, v65
	v_cvt_pk_bf16_f32 v86, v64, v65
	v_mul_f32_e32 v64, v118, v105
	v_mul_f32_e32 v65, v118, v67
	v_mul_f32_e32 v64, v26, v64
	v_mul_f32_e32 v65, v27, v65
	v_cvt_pk_bf16_f32 v87, v64, v65
	v_mul_f32_e32 v64, v118, v106
	v_mul_f32_e32 v65, v118, v68
	v_mul_f32_e32 v64, v20, v64
	v_mul_f32_e32 v65, v21, v65
	v_cvt_pk_bf16_f32 v64, v64, v65
	v_mul_f32_e32 v65, v118, v107
	v_mul_f32_e32 v66, v118, v69
	v_mul_f32_e32 v65, v22, v65
	v_mul_f32_e32 v66, v23, v66
	v_cvt_pk_bf16_f32 v65, v65, v66
	v_mul_f32_e32 v66, v118, v108
	v_mul_f32_e32 v67, v118, v70
	v_mul_f32_e32 v66, v16, v66
	v_mul_f32_e32 v67, v17, v67
	v_cvt_pk_bf16_f32 v66, v66, v67
	v_mul_f32_e32 v67, v118, v109
	v_mul_f32_e32 v68, v118, v71
	v_mul_f32_e32 v67, v18, v67
	v_mul_f32_e32 v68, v19, v68
	v_cvt_pk_bf16_f32 v67, v67, v68
	v_mul_f32_e32 v68, v118, v110
	v_mul_f32_e32 v69, v118, v111
	v_mul_f32_e32 v68, v12, v68
	v_mul_f32_e32 v69, v13, v69
	v_cvt_pk_bf16_f32 v68, v68, v69
	v_mul_f32_e32 v69, v118, v112
	v_mul_f32_e32 v70, v118, v113
	v_mul_f32_e32 v69, v14, v69
	v_mul_f32_e32 v70, v15, v70
	v_cvt_pk_bf16_f32 v69, v69, v70
	v_mul_f32_e32 v70, v118, v114
	v_mul_f32_e32 v71, v118, v115
	v_mul_f32_e32 v70, v8, v70
	v_mul_f32_e32 v71, v9, v71
	v_cvt_pk_bf16_f32 v70, v70, v71
	v_mul_f32_e32 v71, v118, v116
	v_mul_f32_e32 v92, v118, v92
	v_mul_f32_e32 v71, v10, v71
	v_mul_f32_e32 v100, v118, v117
	v_mul_f32_e32 v96, v118, v96
	v_mul_f32_e32 v92, v5, v92
	v_mul_f32_e32 v100, v11, v100
	v_cvt_pk_bf16_f32 v71, v71, v100
	v_mul_f32_e32 v96, v4, v96
	v_cvt_pk_bf16_f32 v104, v96, v92
	v_mul_f32_e32 v92, v118, v97
	v_mul_f32_e32 v93, v118, v93
	v_mul_f32_e32 v92, v6, v92
	v_mul_f32_e32 v93, v7, v93
	v_cvt_pk_bf16_f32 v105, v92, v93
	v_mul_f32_e32 v92, v118, v98
	v_mul_f32_e32 v93, v118, v94
	v_mul_f32_e32 v92, v0, v92
	v_mul_f32_e32 v93, v1, v93
	v_cvt_pk_bf16_f32 v106, v92, v93
	v_mul_f32_e32 v92, v118, v99
	v_mul_f32_e32 v93, v118, v95
	v_mul_f32_e32 v92, v2, v92
	v_mul_f32_e32 v93, v3, v93
	v_cvt_pk_bf16_f32 v107, v92, v93
	ds_write_b128 v249, v[72:75]
	ds_write_b128 v249, v[76:79] offset:8192
	ds_write_b128 v249, v[80:83] offset:16384
	ds_write_b128 v249, v[88:91] offset:24576
	s_waitcnt lgkmcnt(0)
	s_barrier
	buffer_load_dwordx4 v[72:75], v208, s[40:43], s16 offen
	s_add_i32 s16, s14, 0x30e62000
	buffer_load_dwordx4 v[76:79], v208, s[40:43], s16 offen
	s_add_i32 s16, s14, 0x30e64000
	buffer_load_dwordx4 v[80:83], v208, s[40:43], s16 offen
	s_add_i32 s16, s14, 0x30e66000
	buffer_load_dwordx4 v[88:91], v208, s[40:43], s16 offen
	s_waitcnt lgkmcnt(0)
	s_nop 7
	ds_read_b128 v[210:213], v247
	ds_read_b128 v[224:227], v247 offset:512
	ds_read_b128 v[184:187], v248 offset:64
	ds_read_b128 v[228:231], v247 offset:1024
	ds_read_b128 v[96:99], v248
	s_waitcnt lgkmcnt(4)
	v_mfma_f32_16x16x32_bf16 v[92:95], v[210:213], v[84:87], 0
	ds_read_b128 v[210:213], v247 offset:1536
	s_waitcnt lgkmcnt(4)
	v_mfma_f32_16x16x32_bf16 v[92:95], v[224:227], v[64:67], v[92:95]
	ds_read_b128 v[224:227], v247 offset:4096
	s_waitcnt lgkmcnt(3)
	v_mfma_f32_16x16x32_bf16 v[92:95], v[228:231], v[68:71], v[92:95]
	ds_read_b128 v[228:231], v247 offset:4608
	s_waitcnt lgkmcnt(2)
	v_mfma_f32_16x16x32_bf16 v[92:95], v[210:213], v[104:107], v[92:95]
	ds_read_b128 v[210:213], v247 offset:5120
	s_nop 6
	v_pk_mul_f32 v[214:215], v[94:95], v[98:99]
	v_pk_mul_f32 v[216:217], v[92:93], v[96:97]
	s_waitcnt lgkmcnt(2)
	v_mfma_f32_16x16x32_bf16 v[92:95], v[224:227], v[84:87], 0
	ds_read_b128 v[224:227], v247 offset:5632
	s_waitcnt lgkmcnt(2)
	v_mfma_f32_16x16x32_bf16 v[92:95], v[228:231], v[64:67], v[92:95]
	s_waitcnt lgkmcnt(1)
	v_mfma_f32_16x16x32_bf16 v[92:95], v[210:213], v[68:71], v[92:95]
	s_waitcnt lgkmcnt(0)
	v_mfma_f32_16x16x32_bf16 v[176:179], v[224:227], v[104:107], v[92:95]
	s_nop 7
	s_nop 0
	s_add_i32 s16, s14, 0x30e80000
	ds_write_b128 v249, v[48:51] offset:32768
	ds_write_b128 v249, v[52:55] offset:40960
	ds_write_b128 v249, v[56:59] offset:49152
	ds_write_b128 v249, v[60:63] offset:57344
	s_waitcnt lgkmcnt(0)
	s_barrier
	buffer_load_dwordx4 v[48:51], v208, s[40:43], s16 offen
	s_add_i32 s16, s14, 0x30e82000
	buffer_load_dwordx4 v[52:55], v208, s[40:43], s16 offen
	s_add_i32 s16, s14, 0x30e84000
	buffer_load_dwordx4 v[56:59], v208, s[40:43], s16 offen
	s_add_i32 s16, s14, 0x30e86000
	buffer_load_dwordx4 v[92:95], v208, s[40:43], s16 offen
	s_waitcnt lgkmcnt(0)
	s_nop 7
	ds_read_b128 v[210:213], v247 offset:32768
	ds_read_b128 v[224:227], v247 offset:33280
	ds_read_b128 v[228:231], v247 offset:33792
	ds_read_b128 v[168:171], v248 offset:512
	ds_read_b128 v[180:183], v248 offset:576
	s_waitcnt lgkmcnt(4)
	v_mfma_f32_16x16x32_bf16 v[60:63], v[210:213], v[84:87], 0
	ds_read_b128 v[210:213], v247 offset:34304
	s_waitcnt lgkmcnt(4)
	v_mfma_f32_16x16x32_bf16 v[60:63], v[224:227], v[64:67], v[60:63]
	ds_read_b128 v[224:227], v247 offset:36864
	s_waitcnt lgkmcnt(4)
	v_mfma_f32_16x16x32_bf16 v[60:63], v[228:231], v[68:71], v[60:63]
	ds_read_b128 v[228:231], v247 offset:37376
	s_waitcnt lgkmcnt(2)
	v_mfma_f32_16x16x32_bf16 v[164:167], v[210:213], v[104:107], v[60:63]
	ds_read_b128 v[210:213], v247 offset:37888
	s_waitcnt lgkmcnt(2)
	v_mfma_f32_16x16x32_bf16 v[60:63], v[224:227], v[84:87], 0
	ds_read_b128 v[224:227], v247 offset:38400
	s_waitcnt lgkmcnt(2)
	v_mfma_f32_16x16x32_bf16 v[60:63], v[228:231], v[64:67], v[60:63]
	s_waitcnt lgkmcnt(1)
	v_mfma_f32_16x16x32_bf16 v[60:63], v[210:213], v[68:71], v[60:63]
	s_waitcnt lgkmcnt(0)
	v_mfma_f32_16x16x32_bf16 v[172:175], v[224:227], v[104:107], v[60:63]
	s_nop 7
	s_nop 0
	s_add_i32 s16, s14, 0x30ea0000
	ds_write_b128 v249, v[32:35]
	ds_write_b128 v249, v[36:39] offset:8192
	ds_write_b128 v249, v[40:43] offset:16384
	ds_write_b128 v249, v[44:47] offset:24576
	s_waitcnt lgkmcnt(0)
	s_barrier
; #define LAS __attribute__((address_space(3)))
; #define MFMA16(a, b, c) __builtin_amdgcn_mfma_f32_16x16x32_bf16((a), (b), (c), 0, 0, 0)
; #define SCHED_FENCE() __builtin_amdgcn_sched_barrier(0)
; #define NA_ISSUE(seq_, slot_) do { _Pragma("unroll") for (int j = 0; j < 4; ++j) st[slot_][j] = bld<u32x4>(R, co, ((seq_) < 8 ? (unsigned)WS_KB + rowb + (unsigned)((seq_) * 131072) : OFF_VT + rowb + (unsigned)(((seq_) - 8) * 131072)) + (unsigned)j * 8192u); } while (0)
; #define NA_WRITE(slot_, buf_) do { _Pragma("unroll") for (int j = 0; j < 4; ++j) *(LAS u32x4*)(lds + (buf_) * NA_BUF + j * 8192 + tid * 16) = st[slot_][j]; } while (0)
; __device__ __forceinline__ void na_attn_block(LAS unsigned char* lds, rsrc_t R, int l, int bx, int G, int tid, int lane, int wave) {
;     ...
;         for (int a = 0; a < 8; ++a) {
;             NA_ISSUE(a + 3, a % 3);
;             SCHED_FENCE();
;             const int buf = (a & 1) * NA_BUF;
; #pragma unroll
;             for (int t = 0; t < 2; ++t) {
;                 f32x4 acc = (f32x4){0.f, 0.f, 0.f, 0.f};
; #pragma unroll
;                 for (int ks = 0; ks < 4; ++ks) { const bf16x8 kf = *(const LAS bf16x8*)(lds + kfb + buf + t * 4096 + ks * 512); acc = MFMA16(kf, qf[ks], acc); }
;                 const f32x4 rk = *(const LAS f32x4*)(lds + skb + a * 512 + t * 64);
;                 S[a][t] = acc * rk;
;             }
;             SCHED_FENCE();
;             NA_WRITE((a + 1) % 3, (a + 1) & 1);
;             __syncthreads();
	buffer_load_dwordx4 v[32:35], v208, s[40:43], s16 offen
	s_add_i32 s16, s14, 0x30ea2000
	buffer_load_dwordx4 v[40:43], v208, s[40:43], s16 offen
	s_add_i32 s16, s14, 0x30ea4000
	buffer_load_dwordx4 v[60:63], v208, s[40:43], s16 offen
	s_add_i32 s16, s14, 0x30ea6000
	buffer_load_dwordx4 v[96:99], v208, s[40:43], s16 offen
	s_waitcnt lgkmcnt(0)
	s_nop 7
	ds_read_b128 v[210:213], v247
	ds_read_b128 v[224:227], v247 offset:512
	ds_read_b128 v[228:231], v247 offset:1024
	ds_read_b128 v[152:155], v248 offset:1024
	ds_read_b128 v[160:163], v248 offset:1088
	s_waitcnt lgkmcnt(4)
	v_mfma_f32_16x16x32_bf16 v[36:39], v[210:213], v[84:87], 0
	ds_read_b128 v[210:213], v247 offset:1536
	s_waitcnt lgkmcnt(4)
	v_mfma_f32_16x16x32_bf16 v[36:39], v[224:227], v[64:67], v[36:39]
	ds_read_b128 v[224:227], v247 offset:4096
	s_waitcnt lgkmcnt(4)
	v_mfma_f32_16x16x32_bf16 v[36:39], v[228:231], v[68:71], v[36:39]
	ds_read_b128 v[228:231], v247 offset:4608
	s_waitcnt lgkmcnt(2)
	v_mfma_f32_16x16x32_bf16 v[148:151], v[210:213], v[104:107], v[36:39]
	ds_read_b128 v[210:213], v247 offset:5120
	s_waitcnt lgkmcnt(2)
	v_mfma_f32_16x16x32_bf16 v[36:39], v[224:227], v[84:87], 0
	ds_read_b128 v[224:227], v247 offset:5632
	s_waitcnt lgkmcnt(2)
	v_mfma_f32_16x16x32_bf16 v[36:39], v[228:231], v[64:67], v[36:39]
	s_waitcnt lgkmcnt(1)
	v_mfma_f32_16x16x32_bf16 v[36:39], v[210:213], v[68:71], v[36:39]
	s_waitcnt lgkmcnt(0)
	v_mfma_f32_16x16x32_bf16 v[156:159], v[224:227], v[104:107], v[36:39]
	s_nop 7
	s_nop 0
	s_add_i32 s16, s14, 0x30ec0000
	s_waitcnt vmcnt(11)
	ds_write_b128 v249, v[72:75] offset:32768
	s_waitcnt vmcnt(10)
	ds_write_b128 v249, v[76:79] offset:40960
	s_waitcnt vmcnt(9)
	ds_write_b128 v249, v[80:83] offset:49152
	s_waitcnt vmcnt(8)
	ds_write_b128 v249, v[88:91] offset:57344
	s_waitcnt lgkmcnt(0)
	s_barrier
	buffer_load_dwordx4 v[36:39], v208, s[40:43], s16 offen
	s_add_i32 s16, s14, 0x30ec2000
	buffer_load_dwordx4 v[44:47], v208, s[40:43], s16 offen
	s_add_i32 s16, s14, 0x30ec4000
	buffer_load_dwordx4 v[72:75], v208, s[40:43], s16 offen
	s_add_i32 s16, s14, 0x30ec6000
	buffer_load_dwordx4 v[76:79], v208, s[40:43], s16 offen
	s_waitcnt lgkmcnt(0)
	s_nop 7
	ds_read_b128 v[210:213], v247 offset:32768
	ds_read_b128 v[224:227], v247 offset:33280
	ds_read_b128 v[228:231], v247 offset:33792
	ds_read_b128 v[132:135], v248 offset:1536
	ds_read_b128 v[144:147], v248 offset:1600
	s_waitcnt lgkmcnt(4)
	v_mfma_f32_16x16x32_bf16 v[80:83], v[210:213], v[84:87], 0
	ds_read_b128 v[210:213], v247 offset:34304
	s_waitcnt lgkmcnt(4)
	v_mfma_f32_16x16x32_bf16 v[80:83], v[224:227], v[64:67], v[80:83]
	ds_read_b128 v[224:227], v247 offset:36864
	s_waitcnt lgkmcnt(4)
	v_mfma_f32_16x16x32_bf16 v[80:83], v[228:231], v[68:71], v[80:83]
	ds_read_b128 v[228:231], v247 offset:37376
	s_waitcnt lgkmcnt(2)
	v_mfma_f32_16x16x32_bf16 v[128:131], v[210:213], v[104:107], v[80:83]
	ds_read_b128 v[210:213], v247 offset:37888
	s_waitcnt lgkmcnt(2)
	v_mfma_f32_16x16x32_bf16 v[80:83], v[224:227], v[84:87], 0
	ds_read_b128 v[224:227], v247 offset:38400
	s_waitcnt lgkmcnt(2)
	v_mfma_f32_16x16x32_bf16 v[80:83], v[228:231], v[64:67], v[80:83]
	s_waitcnt lgkmcnt(1)
	v_mfma_f32_16x16x32_bf16 v[80:83], v[210:213], v[68:71], v[80:83]
	s_waitcnt lgkmcnt(0)
	v_mfma_f32_16x16x32_bf16 v[136:139], v[224:227], v[104:107], v[80:83]
	s_nop 7
	s_nop 0
	s_add_i32 s16, s14, 0x30ee0000
	s_waitcnt vmcnt(11)
	ds_write_b128 v249, v[48:51]
	s_waitcnt vmcnt(10)
	ds_write_b128 v249, v[52:55] offset:8192
	s_waitcnt vmcnt(9)
	ds_write_b128 v249, v[56:59] offset:16384
	s_waitcnt vmcnt(8)
	ds_write_b128 v249, v[92:95] offset:24576
	s_waitcnt lgkmcnt(0)
	s_barrier
	buffer_load_dwordx4 v[48:51], v208, s[40:43], s16 offen
	s_add_i32 s16, s14, 0x30ee2000
	buffer_load_dwordx4 v[52:55], v208, s[40:43], s16 offen
	s_add_i32 s16, s14, 0x30ee4000
	buffer_load_dwordx4 v[140:143], v208, s[40:43], s16 offen
	s_add_i32 s16, s14, 0x30ee6000
	buffer_load_dwordx4 v[192:195], v208, s[40:43], s16 offen
	s_waitcnt lgkmcnt(0)
	s_nop 7
	ds_read_b128 v[210:213], v247
	ds_read_b128 v[224:227], v247 offset:512
	ds_read_b128 v[228:231], v247 offset:1024
	ds_read_b128 v[120:123], v248 offset:2048
	ds_read_b128 v[124:127], v248 offset:2112
	s_waitcnt lgkmcnt(4)
	v_mfma_f32_16x16x32_bf16 v[56:59], v[210:213], v[84:87], 0
	ds_read_b128 v[210:213], v247 offset:1536
	s_waitcnt lgkmcnt(4)
	v_mfma_f32_16x16x32_bf16 v[56:59], v[224:227], v[64:67], v[56:59]
	ds_read_b128 v[224:227], v247 offset:4096
	s_waitcnt lgkmcnt(4)
	v_mfma_f32_16x16x32_bf16 v[56:59], v[228:231], v[68:71], v[56:59]
	ds_read_b128 v[228:231], v247 offset:4608
	s_waitcnt lgkmcnt(2)
	v_mfma_f32_16x16x32_bf16 v[116:119], v[210:213], v[104:107], v[56:59]
	ds_read_b128 v[210:213], v247 offset:5120
	s_waitcnt lgkmcnt(2)
	v_mfma_f32_16x16x32_bf16 v[56:59], v[224:227], v[84:87], 0
	ds_read_b128 v[224:227], v247 offset:5632
	s_waitcnt lgkmcnt(2)
	v_mfma_f32_16x16x32_bf16 v[56:59], v[228:231], v[64:67], v[56:59]
	s_waitcnt lgkmcnt(1)
	v_mfma_f32_16x16x32_bf16 v[56:59], v[210:213], v[68:71], v[56:59]
	s_waitcnt lgkmcnt(0)
	v_mfma_f32_16x16x32_bf16 v[112:115], v[224:227], v[104:107], v[56:59]
	s_nop 7
	s_nop 0
	s_add_i32 s16, s14, 0x20e00000
	s_waitcnt vmcnt(11)
	ds_write_b128 v249, v[32:35] offset:32768
	s_waitcnt vmcnt(10)
	ds_write_b128 v249, v[40:43] offset:40960
	s_waitcnt vmcnt(9)
	ds_write_b128 v249, v[60:63] offset:49152
	s_waitcnt vmcnt(8)
	ds_write_b128 v249, v[96:99] offset:57344
	s_waitcnt lgkmcnt(0)
	s_barrier
; #define LAS __attribute__((address_space(3)))
; #define MFMA16(a, b, c) __builtin_amdgcn_mfma_f32_16x16x32_bf16((a), (b), (c), 0, 0, 0)
; #define SCHED_FENCE() __builtin_amdgcn_sched_barrier(0)
; #define NA_ISSUE(seq_, slot_) do { _Pragma("unroll") for (int j = 0; j < 4; ++j) st[slot_][j] = bld<u32x4>(R, co, ((seq_) < 8 ? (unsigned)WS_KB + rowb + (unsigned)((seq_) * 131072) : OFF_VT + rowb + (unsigned)(((seq_) - 8) * 131072)) + (unsigned)j * 8192u); } while (0)
; #define NA_WRITE(slot_, buf_) do { _Pragma("unroll") for (int j = 0; j < 4; ++j) *(LAS u32x4*)(lds + (buf_) * NA_BUF + j * 8192 + tid * 16) = st[slot_][j]; } while (0)
; __device__ __forceinline__ void na_attn_block(LAS unsigned char* lds, rsrc_t R, int l, int bx, int G, int tid, int lane, int wave) {
;     ...
;         for (int a = 0; a < 8; ++a) {
;             NA_ISSUE(a + 3, a % 3);
;             SCHED_FENCE();
;             const int buf = (a & 1) * NA_BUF;
; #pragma unroll
;             for (int t = 0; t < 2; ++t) {
;                 f32x4 acc = (f32x4){0.f, 0.f, 0.f, 0.f};
; #pragma unroll
;                 for (int ks = 0; ks < 4; ++ks) { const bf16x8 kf = *(const LAS bf16x8*)(lds + kfb + buf + t * 4096 + ks * 512); acc = MFMA16(kf, qf[ks], acc); }
;                 const f32x4 rk = *(const LAS f32x4*)(lds + skb + a * 512 + t * 64);
;                 S[a][t] = acc * rk;
;             }
;             SCHED_FENCE();
;             NA_WRITE((a + 1) % 3, (a + 1) & 1);
;             __syncthreads();
;         }
;         { const int rowidx0 = start - r + 7;
	buffer_load_dwordx4 v[188:191], v208, s[40:43], s16 offen
	s_add_i32 s16, s14, 0x20e02000
	buffer_load_dwordx4 v[196:199], v208, s[40:43], s16 offen
	s_add_i32 s16, s14, 0x20e04000
	buffer_load_dwordx4 v[200:203], v208, s[40:43], s16 offen
	s_add_i32 s16, s14, 0x20e06000
	buffer_load_dwordx4 v[204:207], v208, s[40:43], s16 offen
	s_waitcnt lgkmcnt(0)
	s_nop 7
	ds_read_b128 v[210:213], v247 offset:32768
	ds_read_b128 v[224:227], v247 offset:33280
	ds_read_b128 v[228:231], v247 offset:33792
	ds_read_b128 v[96:99], v248 offset:2560
	ds_read_b128 v[108:111], v248 offset:2624
	s_waitcnt lgkmcnt(4)
	v_mfma_f32_16x16x32_bf16 v[32:35], v[210:213], v[84:87], 0
	ds_read_b128 v[210:213], v247 offset:34304
	s_waitcnt lgkmcnt(4)
	v_mfma_f32_16x16x32_bf16 v[32:35], v[224:227], v[64:67], v[32:35]
	ds_read_b128 v[224:227], v247 offset:36864
	s_waitcnt lgkmcnt(4)
	v_mfma_f32_16x16x32_bf16 v[32:35], v[228:231], v[68:71], v[32:35]
	ds_read_b128 v[228:231], v247 offset:37376
	s_waitcnt lgkmcnt(2)
	v_mfma_f32_16x16x32_bf16 v[92:95], v[210:213], v[104:107], v[32:35]
	ds_read_b128 v[210:213], v247 offset:37888
	s_waitcnt lgkmcnt(2)
	v_mfma_f32_16x16x32_bf16 v[32:35], v[224:227], v[84:87], 0
	ds_read_b128 v[224:227], v247 offset:38400
	s_waitcnt lgkmcnt(2)
	v_mfma_f32_16x16x32_bf16 v[32:35], v[228:231], v[64:67], v[32:35]
	s_waitcnt lgkmcnt(1)
	v_mfma_f32_16x16x32_bf16 v[32:35], v[210:213], v[68:71], v[32:35]
	s_waitcnt lgkmcnt(0)
	v_mfma_f32_16x16x32_bf16 v[100:103], v[224:227], v[104:107], v[32:35]
	s_nop 7
	s_nop 0
	s_add_i32 s16, s14, 0x20e20000
	s_waitcnt vmcnt(11)
	ds_write_b128 v249, v[36:39]
	s_waitcnt vmcnt(10)
	ds_write_b128 v249, v[44:47] offset:8192
	s_waitcnt vmcnt(9)
	ds_write_b128 v249, v[72:75] offset:16384
	s_waitcnt vmcnt(8)
	ds_write_b128 v249, v[76:79] offset:24576
	s_waitcnt lgkmcnt(0)
	s_barrier
	buffer_load_dwordx4 v[32:35], v208, s[40:43], s16 offen
	s_add_i32 s16, s14, 0x20e22000
	buffer_load_dwordx4 v[40:43], v208, s[40:43], s16 offen
	s_add_i32 s16, s14, 0x20e24000
	buffer_load_dwordx4 v[44:47], v208, s[40:43], s16 offen
	s_add_i32 s16, s14, 0x20e26000
	buffer_load_dwordx4 v[56:59], v208, s[40:43], s16 offen
	s_waitcnt lgkmcnt(0)
	s_nop 7
	ds_read_b128 v[210:213], v247
	ds_read_b128 v[224:227], v247 offset:512
	ds_read_b128 v[228:231], v247 offset:1024
	ds_read_b128 v[76:79], v248 offset:3072
	ds_read_b128 v[88:91], v248 offset:3136
	s_waitcnt lgkmcnt(4)
	v_mfma_f32_16x16x32_bf16 v[36:39], v[210:213], v[84:87], 0
	ds_read_b128 v[210:213], v247 offset:1536
	s_waitcnt lgkmcnt(4)
	v_mfma_f32_16x16x32_bf16 v[36:39], v[224:227], v[64:67], v[36:39]
	ds_read_b128 v[224:227], v247 offset:4096
	s_waitcnt lgkmcnt(4)
	v_mfma_f32_16x16x32_bf16 v[36:39], v[228:231], v[68:71], v[36:39]
	ds_read_b128 v[228:231], v247 offset:4608
	s_waitcnt lgkmcnt(2)
	v_mfma_f32_16x16x32_bf16 v[72:75], v[210:213], v[104:107], v[36:39]
	ds_read_b128 v[210:213], v247 offset:5120
	s_waitcnt lgkmcnt(2)
	v_mfma_f32_16x16x32_bf16 v[36:39], v[224:227], v[84:87], 0
	ds_read_b128 v[224:227], v247 offset:5632
	s_waitcnt lgkmcnt(2)
	v_mfma_f32_16x16x32_bf16 v[36:39], v[228:231], v[64:67], v[36:39]
	s_waitcnt lgkmcnt(1)
	v_mfma_f32_16x16x32_bf16 v[36:39], v[210:213], v[68:71], v[36:39]
	s_waitcnt lgkmcnt(0)
	v_mfma_f32_16x16x32_bf16 v[80:83], v[224:227], v[104:107], v[36:39]
	s_nop 7
	s_nop 0
	s_add_i32 s16, s14, 0x20e40000
	s_waitcnt vmcnt(11)
	ds_write_b128 v249, v[48:51] offset:32768
	s_waitcnt vmcnt(10)
	ds_write_b128 v249, v[52:55] offset:40960
	s_waitcnt vmcnt(9)
	ds_write_b128 v249, v[140:143] offset:49152
	s_waitcnt vmcnt(8)
	ds_write_b128 v249, v[192:195] offset:57344
	s_waitcnt lgkmcnt(0)
	s_barrier
	buffer_load_dwordx4 v[36:39], v208, s[40:43], s16 offen
	s_add_i32 s16, s14, 0x20e42000
	buffer_load_dwordx4 v[48:51], v208, s[40:43], s16 offen
	s_add_i32 s16, s14, 0x20e44000
	buffer_load_dwordx4 v[52:55], v208, s[40:43], s16 offen
	s_add_i32 s16, s14, 0x20e46000
	buffer_load_dwordx4 v[60:63], v208, s[40:43], s16 offen
	s_waitcnt lgkmcnt(0)
	s_nop 7
	ds_read_b128 v[210:213], v247 offset:32768
	ds_read_b128 v[224:227], v247 offset:36864
	ds_read_b128 v[228:231], v247 offset:33280
	s_waitcnt lgkmcnt(2)
	v_mfma_f32_16x16x32_bf16 v[140:143], v[210:213], v[84:87], 0
	ds_read_b128 v[210:213], v247 offset:33792
	s_waitcnt lgkmcnt(2)
	v_mfma_f32_16x16x32_bf16 v[192:195], v[224:227], v[84:87], 0
	ds_read_b128 v[224:227], v247 offset:34304
	s_waitcnt lgkmcnt(2)
	v_mfma_f32_16x16x32_bf16 v[84:87], v[228:231], v[64:67], v[140:143]
	ds_read_b128 v[228:231], v247 offset:37376
	s_nop 0
	ds_read_b128 v[140:143], v248 offset:3584
	s_waitcnt lgkmcnt(3)
	v_mfma_f32_16x16x32_bf16 v[84:87], v[210:213], v[68:71], v[84:87]
	ds_read_b128 v[210:213], v247 offset:37888
	s_waitcnt lgkmcnt(3)
	v_mfma_f32_16x16x32_bf16 v[84:87], v[224:227], v[104:107], v[84:87]
	ds_read_b128 v[224:227], v247 offset:38400
	s_waitcnt lgkmcnt(3)
	v_mfma_f32_16x16x32_bf16 v[64:67], v[228:231], v[64:67], v[192:195]
	s_waitcnt lgkmcnt(1)
	v_mfma_f32_16x16x32_bf16 v[68:71], v[210:213], v[68:71], v[64:67]
	s_nop 5
	ds_read_b128 v[64:67], v248 offset:3648
	s_waitcnt lgkmcnt(1)
	v_mfma_f32_16x16x32_bf16 v[68:71], v[224:227], v[104:107], v[68:71]
	s_waitcnt lgkmcnt(0)
	s_nop 6
	s_nop 0
	s_mul_i32 s3, s3, 15
	s_sub_i32 s16, s3, s2
	s_add_i32 s16, s16, 7
	s_add_i32 s15, s16, s15
	s_mul_i32 s15, s15, 31
	s_waitcnt vmcnt(11)
	ds_write_b128 v249, v[188:191]
	s_waitcnt vmcnt(10)
	ds_write_b128 v249, v[196:199] offset:8192
	s_waitcnt vmcnt(9)
	ds_write_b128 v249, v[200:203] offset:16384
	s_waitcnt vmcnt(8)
	ds_write_b128 v249, v[204:207] offset:24576
	s_add_i32 s17, s15, 15
	v_mov_b32_e32 v188, 0xf149f2ca
	v_mov_b32_e32 v189, 0xf149f2ca
	s_waitcnt lgkmcnt(0)
	s_barrier
; #define LAS __attribute__((address_space(3)))
; __device__ __forceinline__ void na_attn_block(LAS unsigned char* lds, rsrc_t R, int l, int bx, int G, int tid, int lane, int wave) {
;     ...
;         { const int rowidx0 = start - r + 7;
; #pragma unroll
;           for (int a = 0; a < 8; ++a)
; #pragma unroll
;               for (int q = 0; q < 8; ++q) { const int kcol = kc0 + 16 * (q >> 2) + 4 * kq + (q & 3); const bool valid = (kcol >= cs) && (kcol < cs + 16);
;                   int ci = kcol - qcol + 15; ci = ci < 0 ? 0 : (ci > 30 ? 30 : ci);
;                   const float bias = *(const LAS float*)(lds + NA_RPB + ((h * 15 + rowidx0 + a) * 31 + ci) * 4);
;                   S[a][q >> 2][q & 3] = valid ? S[a][q >> 2][q & 3] + bias : -1e30f; } }
	v_add_u32_e32 v210, s17, v238
	v_lshl_add_u32 v210, v210, 2, 0
	v_add_u32_e32 v210, 0x11000, v210
	ds_read_b32 v210, v210
	v_add_u32_e32 v211, s17, v239
	v_lshl_add_u32 v211, v211, 2, 0
	v_add_u32_e32 v211, 0x11000, v211
	ds_read_b32 v211, v211
	v_add_u32_e32 v212, s17, v240
	v_lshl_add_u32 v212, v212, 2, 0
	v_add_u32_e32 v212, 0x11000, v212
	ds_read_b32 v212, v212
	v_add_u32_e32 v213, s17, v241
	v_lshl_add_u32 v213, v213, 2, 0
	v_add_u32_e32 v213, 0x11000, v213
	ds_read_b32 v213, v213
	v_add_u32_e32 v224, s17, v242
	v_lshl_add_u32 v224, v224, 2, 0
	v_add_u32_e32 v224, 0x11000, v224
	ds_read_b32 v224, v224
	v_add_u32_e32 v225, s17, v243
	v_lshl_add_u32 v225, v225, 2, 0
	v_add_u32_e32 v225, 0x11000, v225
	ds_read_b32 v225, v225
	v_add_u32_e32 v226, s17, v244
	v_lshl_add_u32 v226, v226, 2, 0
	v_add_u32_e32 v226, 0x11000, v226
	ds_read_b32 v226, v226
	v_add_u32_e32 v227, s17, v245
	v_lshl_add_u32 v227, v227, 2, 0
	v_add_u32_e32 v227, 0x11000, v227
	ds_read_b32 v227, v227
	s_waitcnt lgkmcnt(7)
	v_add_f32_e32 v210, v216, v210
	v_cndmask_b32_e64 v189, v189, v210, s[6:7]
	s_waitcnt lgkmcnt(6)
	v_add_f32_e32 v211, v217, v211
	v_cndmask_b32_e64 v188, v188, v211, s[22:23]
	v_mov_b32_e32 v190, 0xf149f2ca
	v_mov_b32_e32 v191, 0xf149f2ca
	s_waitcnt lgkmcnt(5)
	v_add_f32_e32 v212, v214, v212
	v_cndmask_b32_e64 v191, v191, v212, s[28:29]
	s_waitcnt lgkmcnt(4)
	v_add_f32_e32 v213, v215, v213
	v_cndmask_b32_e64 v190, v190, v213, s[30:31]
	v_pk_mul_f32 v[104:105], v[178:179], v[186:187]
	v_pk_mul_f32 v[106:107], v[176:177], v[184:185]
	v_mov_b32_e32 v176, 0xf149f2ca
	v_mov_b32_e32 v177, 0xf149f2ca
	s_waitcnt lgkmcnt(3)
	v_add_f32_e32 v224, v106, v224
	v_cndmask_b32_e64 v177, v177, v224, s[36:37]
	s_waitcnt lgkmcnt(2)
	v_add_f32_e32 v225, v107, v225
	v_cndmask_b32_e64 v176, v176, v225, s[38:39]
	v_mov_b32_e32 v178, 0xf149f2ca
	v_mov_b32_e32 v179, 0xf149f2ca
	s_waitcnt lgkmcnt(1)
	v_add_f32_e32 v226, v104, v226
	v_cndmask_b32_e64 v179, v179, v226, s[44:45]
	s_waitcnt lgkmcnt(0)
	v_add_f32_e32 v227, v105, v227
	v_cndmask_b32_e64 v178, v178, v227, s[0:1]
	v_pk_mul_f32 v[104:105], v[166:167], v[170:171]
	v_pk_mul_f32 v[106:107], v[164:165], v[168:169]
	s_add_i32 s17, s15, 46
	v_mov_b32_e32 v164, 0xf149f2ca
	v_mov_b32_e32 v165, 0xf149f2ca
	v_add_u32_e32 v210, s17, v238
	v_lshl_add_u32 v210, v210, 2, 0
	v_add_u32_e32 v210, 0x11000, v210
	ds_read_b32 v210, v210
	v_add_u32_e32 v211, s17, v239
	v_lshl_add_u32 v211, v211, 2, 0
	v_add_u32_e32 v211, 0x11000, v211
	ds_read_b32 v211, v211
	v_add_u32_e32 v212, s17, v240
	v_lshl_add_u32 v212, v212, 2, 0
	v_add_u32_e32 v212, 0x11000, v212
	ds_read_b32 v212, v212
	v_add_u32_e32 v213, s17, v241
	v_lshl_add_u32 v213, v213, 2, 0
	v_add_u32_e32 v213, 0x11000, v213
	ds_read_b32 v213, v213
	v_add_u32_e32 v224, s17, v242
	v_lshl_add_u32 v224, v224, 2, 0
	v_add_u32_e32 v224, 0x11000, v224
	ds_read_b32 v224, v224
	v_add_u32_e32 v225, s17, v243
	v_lshl_add_u32 v225, v225, 2, 0
	v_add_u32_e32 v225, 0x11000, v225
	ds_read_b32 v225, v225
	v_add_u32_e32 v226, s17, v244
	v_lshl_add_u32 v226, v226, 2, 0
	v_add_u32_e32 v226, 0x11000, v226
	ds_read_b32 v226, v226
	v_add_u32_e32 v227, s17, v245
	v_lshl_add_u32 v227, v227, 2, 0
	v_add_u32_e32 v227, 0x11000, v227
	ds_read_b32 v227, v227
	s_waitcnt lgkmcnt(7)
	v_add_f32_e32 v210, v106, v210
	v_cndmask_b32_e64 v165, v165, v210, s[6:7]
	s_waitcnt lgkmcnt(6)
	v_add_f32_e32 v211, v107, v211
	v_cndmask_b32_e64 v164, v164, v211, s[22:23]
	v_mov_b32_e32 v166, 0xf149f2ca
	v_mov_b32_e32 v167, 0xf149f2ca
	s_waitcnt lgkmcnt(5)
	v_add_f32_e32 v212, v104, v212
	v_cndmask_b32_e64 v167, v167, v212, s[28:29]
	s_waitcnt lgkmcnt(4)
	v_add_f32_e32 v213, v105, v213
	v_cndmask_b32_e64 v166, v166, v213, s[30:31]
	v_pk_mul_f32 v[104:105], v[174:175], v[182:183]
	v_pk_mul_f32 v[106:107], v[172:173], v[180:181]
	v_mov_b32_e32 v168, 0xf149f2ca
	v_mov_b32_e32 v169, 0xf149f2ca
	s_waitcnt lgkmcnt(3)
	v_add_f32_e32 v224, v106, v224
	v_cndmask_b32_e64 v169, v169, v224, s[36:37]
	s_waitcnt lgkmcnt(2)
	v_add_f32_e32 v225, v107, v225
	v_cndmask_b32_e64 v168, v168, v225, s[38:39]
	v_mov_b32_e32 v170, 0xf149f2ca
	v_mov_b32_e32 v171, 0xf149f2ca
	s_waitcnt lgkmcnt(1)
	v_add_f32_e32 v226, v104, v226
	v_cndmask_b32_e64 v171, v171, v226, s[44:45]
	s_waitcnt lgkmcnt(0)
	v_add_f32_e32 v227, v105, v227
	v_cndmask_b32_e64 v170, v170, v227, s[0:1]
	v_pk_mul_f32 v[104:105], v[150:151], v[154:155]
	v_pk_mul_f32 v[106:107], v[148:149], v[152:153]
	s_add_i32 s17, s15, 0x4d
	v_mov_b32_e32 v148, 0xf149f2ca
	v_mov_b32_e32 v149, 0xf149f2ca
	v_add_u32_e32 v210, s17, v238
	v_lshl_add_u32 v210, v210, 2, 0
	v_add_u32_e32 v210, 0x11000, v210
	ds_read_b32 v210, v210
	v_add_u32_e32 v211, s17, v239
	v_lshl_add_u32 v211, v211, 2, 0
	v_add_u32_e32 v211, 0x11000, v211
	ds_read_b32 v211, v211
	v_add_u32_e32 v212, s17, v240
	v_lshl_add_u32 v212, v212, 2, 0
	v_add_u32_e32 v212, 0x11000, v212
	ds_read_b32 v212, v212
	v_add_u32_e32 v213, s17, v241
	v_lshl_add_u32 v213, v213, 2, 0
	v_add_u32_e32 v213, 0x11000, v213
	ds_read_b32 v213, v213
	v_add_u32_e32 v224, s17, v242
	v_lshl_add_u32 v224, v224, 2, 0
	v_add_u32_e32 v224, 0x11000, v224
	ds_read_b32 v224, v224
	v_add_u32_e32 v225, s17, v243
	v_lshl_add_u32 v225, v225, 2, 0
	v_add_u32_e32 v225, 0x11000, v225
	ds_read_b32 v225, v225
	v_add_u32_e32 v226, s17, v244
	v_lshl_add_u32 v226, v226, 2, 0
	v_add_u32_e32 v226, 0x11000, v226
	ds_read_b32 v226, v226
	v_add_u32_e32 v227, s17, v245
	v_lshl_add_u32 v227, v227, 2, 0
	v_add_u32_e32 v227, 0x11000, v227
	ds_read_b32 v227, v227
	s_waitcnt lgkmcnt(7)
	v_add_f32_e32 v210, v106, v210
	v_cndmask_b32_e64 v149, v149, v210, s[6:7]
	s_waitcnt lgkmcnt(6)
; #define LAS __attribute__((address_space(3)))
; __device__ __forceinline__ void na_attn_block(LAS unsigned char* lds, rsrc_t R, int l, int bx, int G, int tid, int lane, int wave) {
;     ...
;         { const int rowidx0 = start - r + 7;
; #pragma unroll
;           for (int a = 0; a < 8; ++a)
; #pragma unroll
;               for (int q = 0; q < 8; ++q) { const int kcol = kc0 + 16 * (q >> 2) + 4 * kq + (q & 3); const bool valid = (kcol >= cs) && (kcol < cs + 16);
;                   int ci = kcol - qcol + 15; ci = ci < 0 ? 0 : (ci > 30 ? 30 : ci);
;                   const float bias = *(const LAS float*)(lds + NA_RPB + ((h * 15 + rowidx0 + a) * 31 + ci) * 4);
;                   S[a][q >> 2][q & 3] = valid ? S[a][q >> 2][q & 3] + bias : -1e30f; } }
	v_add_f32_e32 v211, v107, v211
	v_cndmask_b32_e64 v148, v148, v211, s[22:23]
	v_mov_b32_e32 v150, 0xf149f2ca
	v_mov_b32_e32 v151, 0xf149f2ca
	s_waitcnt lgkmcnt(5)
	v_add_f32_e32 v212, v104, v212
	v_cndmask_b32_e64 v151, v151, v212, s[28:29]
	s_waitcnt lgkmcnt(4)
	v_add_f32_e32 v213, v105, v213
	v_cndmask_b32_e64 v150, v150, v213, s[30:31]
	v_pk_mul_f32 v[104:105], v[158:159], v[162:163]
	v_pk_mul_f32 v[106:107], v[156:157], v[160:161]
	v_mov_b32_e32 v152, 0xf149f2ca
	v_mov_b32_e32 v153, 0xf149f2ca
	s_waitcnt lgkmcnt(3)
	v_add_f32_e32 v224, v106, v224
	v_cndmask_b32_e64 v153, v153, v224, s[36:37]
	s_waitcnt lgkmcnt(2)
	v_add_f32_e32 v225, v107, v225
	v_cndmask_b32_e64 v152, v152, v225, s[38:39]
	v_mov_b32_e32 v154, 0xf149f2ca
	v_mov_b32_e32 v155, 0xf149f2ca
	s_waitcnt lgkmcnt(1)
	v_add_f32_e32 v226, v104, v226
	v_cndmask_b32_e64 v155, v155, v226, s[44:45]
	s_waitcnt lgkmcnt(0)
	v_add_f32_e32 v227, v105, v227
	v_cndmask_b32_e64 v154, v154, v227, s[0:1]
	v_pk_mul_f32 v[104:105], v[130:131], v[134:135]
	v_pk_mul_f32 v[106:107], v[128:129], v[132:133]
	s_add_i32 s17, s15, 0x6c
	v_mov_b32_e32 v128, 0xf149f2ca
	v_mov_b32_e32 v129, 0xf149f2ca
	v_add_u32_e32 v210, s17, v238
	v_lshl_add_u32 v210, v210, 2, 0
	v_add_u32_e32 v210, 0x11000, v210
	ds_read_b32 v210, v210
	v_add_u32_e32 v211, s17, v239
	v_lshl_add_u32 v211, v211, 2, 0
	v_add_u32_e32 v211, 0x11000, v211
	ds_read_b32 v211, v211
	v_add_u32_e32 v212, s17, v240
	v_lshl_add_u32 v212, v212, 2, 0
	v_add_u32_e32 v212, 0x11000, v212
	ds_read_b32 v212, v212
	v_add_u32_e32 v213, s17, v241
	v_lshl_add_u32 v213, v213, 2, 0
	v_add_u32_e32 v213, 0x11000, v213
	ds_read_b32 v213, v213
	v_add_u32_e32 v224, s17, v242
	v_lshl_add_u32 v224, v224, 2, 0
	v_add_u32_e32 v224, 0x11000, v224
	ds_read_b32 v224, v224
	v_add_u32_e32 v225, s17, v243
	v_lshl_add_u32 v225, v225, 2, 0
	v_add_u32_e32 v225, 0x11000, v225
	ds_read_b32 v225, v225
	v_add_u32_e32 v226, s17, v244
	v_lshl_add_u32 v226, v226, 2, 0
	v_add_u32_e32 v226, 0x11000, v226
	ds_read_b32 v226, v226
	v_add_u32_e32 v227, s17, v245
	v_lshl_add_u32 v227, v227, 2, 0
	v_add_u32_e32 v227, 0x11000, v227
	ds_read_b32 v227, v227
	s_waitcnt lgkmcnt(7)
	v_add_f32_e32 v210, v106, v210
	v_cndmask_b32_e64 v129, v129, v210, s[6:7]
	s_waitcnt lgkmcnt(6)
	v_add_f32_e32 v211, v107, v211
	v_cndmask_b32_e64 v128, v128, v211, s[22:23]
	v_mov_b32_e32 v130, 0xf149f2ca
	v_mov_b32_e32 v131, 0xf149f2ca
	s_waitcnt lgkmcnt(5)
	v_add_f32_e32 v212, v104, v212
	v_cndmask_b32_e64 v131, v131, v212, s[28:29]
	s_waitcnt lgkmcnt(4)
	v_add_f32_e32 v213, v105, v213
	v_cndmask_b32_e64 v130, v130, v213, s[30:31]
	v_pk_mul_f32 v[104:105], v[138:139], v[146:147]
	v_pk_mul_f32 v[106:107], v[136:137], v[144:145]
	v_mov_b32_e32 v132, 0xf149f2ca
	v_mov_b32_e32 v133, 0xf149f2ca
	s_waitcnt lgkmcnt(3)
	v_add_f32_e32 v224, v106, v224
	v_cndmask_b32_e64 v133, v133, v224, s[36:37]
	s_waitcnt lgkmcnt(2)
	v_add_f32_e32 v225, v107, v225
	v_cndmask_b32_e64 v132, v132, v225, s[38:39]
	v_mov_b32_e32 v134, 0xf149f2ca
	v_mov_b32_e32 v135, 0xf149f2ca
	s_waitcnt lgkmcnt(1)
	v_add_f32_e32 v226, v104, v226
	v_cndmask_b32_e64 v135, v135, v226, s[44:45]
	s_waitcnt lgkmcnt(0)
	v_add_f32_e32 v227, v105, v227
	v_cndmask_b32_e64 v134, v134, v227, s[0:1]
	v_pk_mul_f32 v[106:107], v[116:117], v[120:121]
	v_add_u32_e32 v116, s16, v250
	v_mul_lo_u32 v116, v116, 31
	v_pk_mul_f32 v[104:105], v[118:119], v[122:123]
	v_add_u32_e32 v120, 15, v116
	v_mov_b32_e32 v116, 0xf149f2ca
	v_mov_b32_e32 v117, 0xf149f2ca
	v_add_u32_e32 v210, v120, v238
	v_lshl_add_u32 v210, v210, 2, 0
	v_add_u32_e32 v210, 0x11000, v210
	ds_read_b32 v210, v210
	v_add_u32_e32 v211, v120, v239
	v_lshl_add_u32 v211, v211, 2, 0
	v_add_u32_e32 v211, 0x11000, v211
	ds_read_b32 v211, v211
	v_add_u32_e32 v212, v120, v240
	v_lshl_add_u32 v212, v212, 2, 0
	v_add_u32_e32 v212, 0x11000, v212
	ds_read_b32 v212, v212
	v_add_u32_e32 v213, v120, v241
	v_lshl_add_u32 v213, v213, 2, 0
	v_add_u32_e32 v213, 0x11000, v213
	ds_read_b32 v213, v213
	v_add_u32_e32 v224, v120, v242
	v_lshl_add_u32 v224, v224, 2, 0
	v_add_u32_e32 v224, 0x11000, v224
	ds_read_b32 v224, v224
	v_add_u32_e32 v225, v120, v243
	v_lshl_add_u32 v225, v225, 2, 0
	v_add_u32_e32 v225, 0x11000, v225
	ds_read_b32 v225, v225
	v_add_u32_e32 v226, v120, v244
	v_lshl_add_u32 v226, v226, 2, 0
	v_add_u32_e32 v226, 0x11000, v226
	ds_read_b32 v226, v226
	v_add_u32_e32 v227, v120, v245
	v_lshl_add_u32 v227, v227, 2, 0
	v_add_u32_e32 v227, 0x11000, v227
	ds_read_b32 v227, v227
	s_waitcnt lgkmcnt(7)
	v_add_f32_e32 v210, v106, v210
	v_cndmask_b32_e64 v117, v117, v210, s[6:7]
	s_waitcnt lgkmcnt(6)
	v_add_f32_e32 v211, v107, v211
	v_cndmask_b32_e64 v116, v116, v211, s[22:23]
	v_mov_b32_e32 v118, 0xf149f2ca
	v_mov_b32_e32 v119, 0xf149f2ca
	s_waitcnt lgkmcnt(5)
	v_add_f32_e32 v212, v104, v212
	v_cndmask_b32_e64 v119, v119, v212, s[28:29]
	s_waitcnt lgkmcnt(4)
	v_add_f32_e32 v213, v105, v213
	v_cndmask_b32_e64 v118, v118, v213, s[30:31]
	v_pk_mul_f32 v[104:105], v[114:115], v[126:127]
	v_pk_mul_f32 v[106:107], v[112:113], v[124:125]
	v_mov_b32_e32 v112, 0xf149f2ca
	v_mov_b32_e32 v113, 0xf149f2ca
	s_waitcnt lgkmcnt(3)
	v_add_f32_e32 v224, v106, v224
	v_cndmask_b32_e64 v113, v113, v224, s[36:37]
	s_waitcnt lgkmcnt(2)
	v_add_f32_e32 v225, v107, v225
	v_cndmask_b32_e64 v112, v112, v225, s[38:39]
	v_mov_b32_e32 v106, 0xf149f2ca
	v_mov_b32_e32 v107, 0xf149f2ca
	s_waitcnt lgkmcnt(1)
	v_add_f32_e32 v226, v104, v226
	v_cndmask_b32_e64 v107, v107, v226, s[44:45]
	s_waitcnt lgkmcnt(0)
; #define LAS __attribute__((address_space(3)))
; __device__ __forceinline__ void na_attn_block(LAS unsigned char* lds, rsrc_t R, int l, int bx, int G, int tid, int lane, int wave) {
;     ...
;         { const int rowidx0 = start - r + 7;
; #pragma unroll
;           for (int a = 0; a < 8; ++a)
; #pragma unroll
;               for (int q = 0; q < 8; ++q) { const int kcol = kc0 + 16 * (q >> 2) + 4 * kq + (q & 3); const bool valid = (kcol >= cs) && (kcol < cs + 16);
;                   int ci = kcol - qcol + 15; ci = ci < 0 ? 0 : (ci > 30 ? 30 : ci);
;                   const float bias = *(const LAS float*)(lds + NA_RPB + ((h * 15 + rowidx0 + a) * 31 + ci) * 4);
;                   S[a][q >> 2][q & 3] = valid ? S[a][q >> 2][q & 3] + bias : -1e30f; } }
	v_add_f32_e32 v227, v105, v227
	v_cndmask_b32_e64 v106, v106, v227, s[0:1]
	v_pk_mul_f32 v[94:95], v[94:95], v[98:99]
	v_pk_mul_f32 v[92:93], v[92:93], v[96:97]
	s_add_i32 s16, s15, 0xaa
	v_mov_b32_e32 v96, 0xf149f2ca
	v_mov_b32_e32 v97, 0xf149f2ca
	v_add_u32_e32 v210, s16, v238
	v_lshl_add_u32 v210, v210, 2, 0
	v_add_u32_e32 v210, 0x11000, v210
	ds_read_b32 v210, v210
	v_add_u32_e32 v211, s16, v239
	v_lshl_add_u32 v211, v211, 2, 0
	v_add_u32_e32 v211, 0x11000, v211
	ds_read_b32 v211, v211
	v_add_u32_e32 v212, s16, v240
	v_lshl_add_u32 v212, v212, 2, 0
	v_add_u32_e32 v212, 0x11000, v212
	ds_read_b32 v212, v212
	v_add_u32_e32 v213, s16, v241
	v_lshl_add_u32 v213, v213, 2, 0
	v_add_u32_e32 v213, 0x11000, v213
	ds_read_b32 v213, v213
	v_add_u32_e32 v224, s16, v242
	v_lshl_add_u32 v224, v224, 2, 0
	v_add_u32_e32 v224, 0x11000, v224
	ds_read_b32 v224, v224
	v_add_u32_e32 v225, s16, v243
	v_lshl_add_u32 v225, v225, 2, 0
	v_add_u32_e32 v225, 0x11000, v225
	ds_read_b32 v225, v225
	v_add_u32_e32 v226, s16, v244
	v_lshl_add_u32 v226, v226, 2, 0
	v_add_u32_e32 v226, 0x11000, v226
	ds_read_b32 v226, v226
	v_add_u32_e32 v227, s16, v245
	v_lshl_add_u32 v227, v227, 2, 0
	v_add_u32_e32 v227, 0x11000, v227
	ds_read_b32 v227, v227
	s_waitcnt lgkmcnt(7)
	v_add_f32_e32 v210, v92, v210
	v_cndmask_b32_e64 v97, v97, v210, s[6:7]
	s_waitcnt lgkmcnt(6)
	v_add_f32_e32 v211, v93, v211
	v_cndmask_b32_e64 v96, v96, v211, s[22:23]
	v_mov_b32_e32 v98, 0xf149f2ca
	v_mov_b32_e32 v99, 0xf149f2ca
	s_waitcnt lgkmcnt(5)
	v_add_f32_e32 v212, v94, v212
	v_cndmask_b32_e64 v99, v99, v212, s[28:29]
	s_waitcnt lgkmcnt(4)
	v_add_f32_e32 v213, v95, v213
	v_cndmask_b32_e64 v98, v98, v213, s[30:31]
	v_pk_mul_f32 v[92:93], v[102:103], v[110:111]
	v_pk_mul_f32 v[94:95], v[100:101], v[108:109]
	v_mov_b32_e32 v100, 0xf149f2ca
	v_mov_b32_e32 v105, 0xf149f2ca
	s_waitcnt lgkmcnt(3)
	v_add_f32_e32 v224, v94, v224
	v_cndmask_b32_e64 v105, v105, v224, s[36:37]
	s_waitcnt lgkmcnt(2)
	v_add_f32_e32 v225, v95, v225
	v_cndmask_b32_e64 v100, v100, v225, s[38:39]
	v_mov_b32_e32 v94, 0xf149f2ca
	v_mov_b32_e32 v95, 0xf149f2ca
	s_waitcnt lgkmcnt(1)
	v_add_f32_e32 v226, v92, v226
	v_cndmask_b32_e64 v95, v95, v226, s[44:45]
	s_waitcnt lgkmcnt(0)
	v_add_f32_e32 v227, v93, v227
	v_cndmask_b32_e64 v94, v94, v227, s[0:1]
	v_pk_mul_f32 v[74:75], v[74:75], v[78:79]
	v_pk_mul_f32 v[72:73], v[72:73], v[76:77]
	s_add_i32 s16, s15, 0xc9
	v_mov_b32_e32 v76, 0xf149f2ca
	v_mov_b32_e32 v77, 0xf149f2ca
	v_add_u32_e32 v210, s16, v238
	v_lshl_add_u32 v210, v210, 2, 0
	v_add_u32_e32 v210, 0x11000, v210
	ds_read_b32 v210, v210
	v_add_u32_e32 v211, s16, v239
	v_lshl_add_u32 v211, v211, 2, 0
	v_add_u32_e32 v211, 0x11000, v211
	ds_read_b32 v211, v211
	v_add_u32_e32 v212, s16, v240
	v_lshl_add_u32 v212, v212, 2, 0
	v_add_u32_e32 v212, 0x11000, v212
	ds_read_b32 v212, v212
	v_add_u32_e32 v213, s16, v241
	v_lshl_add_u32 v213, v213, 2, 0
	v_add_u32_e32 v213, 0x11000, v213
	ds_read_b32 v213, v213
	v_add_u32_e32 v224, s16, v242
	v_lshl_add_u32 v224, v224, 2, 0
	v_add_u32_e32 v224, 0x11000, v224
	ds_read_b32 v224, v224
	v_add_u32_e32 v225, s16, v243
	v_lshl_add_u32 v225, v225, 2, 0
	v_add_u32_e32 v225, 0x11000, v225
	ds_read_b32 v225, v225
	v_add_u32_e32 v226, s16, v244
	v_lshl_add_u32 v226, v226, 2, 0
	v_add_u32_e32 v226, 0x11000, v226
	ds_read_b32 v226, v226
	v_add_u32_e32 v227, s16, v245
	v_lshl_add_u32 v227, v227, 2, 0
	v_add_u32_e32 v227, 0x11000, v227
	ds_read_b32 v227, v227
	s_waitcnt lgkmcnt(7)
	v_add_f32_e32 v210, v72, v210
	v_cndmask_b32_e64 v77, v77, v210, s[6:7]
	s_waitcnt lgkmcnt(6)
	v_add_f32_e32 v211, v73, v211
	v_cndmask_b32_e64 v76, v76, v211, s[22:23]
	v_mov_b32_e32 v78, 0xf149f2ca
	v_mov_b32_e32 v79, 0xf149f2ca
	s_waitcnt lgkmcnt(5)
	v_add_f32_e32 v212, v74, v212
	v_cndmask_b32_e64 v79, v79, v212, s[28:29]
	s_waitcnt lgkmcnt(4)
	v_add_f32_e32 v213, v75, v213
	v_cndmask_b32_e64 v78, v78, v213, s[30:31]
	v_pk_mul_f32 v[72:73], v[82:83], v[90:91]
	v_pk_mul_f32 v[74:75], v[80:81], v[88:89]
	v_mov_b32_e32 v80, 0xf149f2ca
	v_mov_b32_e32 v81, 0xf149f2ca
	s_waitcnt lgkmcnt(3)
	v_add_f32_e32 v224, v74, v224
	v_cndmask_b32_e64 v81, v81, v224, s[36:37]
	s_waitcnt lgkmcnt(2)
	v_add_f32_e32 v225, v75, v225
	v_cndmask_b32_e64 v80, v80, v225, s[38:39]
	v_mov_b32_e32 v82, 0xf149f2ca
	v_mov_b32_e32 v83, 0xf149f2ca
	s_waitcnt lgkmcnt(1)
	v_add_f32_e32 v226, v72, v226
	v_cndmask_b32_e64 v83, v83, v226, s[44:45]
	s_waitcnt lgkmcnt(0)
	v_add_f32_e32 v227, v73, v227
	v_cndmask_b32_e64 v82, v82, v227, s[0:1]
	v_pk_mul_f32 v[72:73], v[86:87], v[142:143]
	v_pk_mul_f32 v[74:75], v[84:85], v[140:141]
	s_addk_i32 s15, 0xe8
	v_mov_b32_e32 v84, 0xf149f2ca
	v_mov_b32_e32 v85, 0xf149f2ca
	v_add_u32_e32 v210, s15, v238
	v_lshl_add_u32 v210, v210, 2, 0
	v_add_u32_e32 v210, 0x11000, v210
	ds_read_b32 v210, v210
	v_add_u32_e32 v211, s15, v239
	v_lshl_add_u32 v211, v211, 2, 0
	v_add_u32_e32 v211, 0x11000, v211
	ds_read_b32 v211, v211
	v_add_u32_e32 v212, s15, v240
	v_lshl_add_u32 v212, v212, 2, 0
	v_add_u32_e32 v212, 0x11000, v212
	ds_read_b32 v212, v212
	v_add_u32_e32 v213, s15, v241
	v_lshl_add_u32 v213, v213, 2, 0
	v_add_u32_e32 v213, 0x11000, v213
	ds_read_b32 v213, v213
	v_add_u32_e32 v224, s15, v242
	v_lshl_add_u32 v224, v224, 2, 0
	v_add_u32_e32 v224, 0x11000, v224
	ds_read_b32 v224, v224
	v_add_u32_e32 v225, s15, v243
	v_lshl_add_u32 v225, v225, 2, 0
	v_add_u32_e32 v225, 0x11000, v225
	ds_read_b32 v225, v225
	v_add_u32_e32 v226, s15, v244
	v_lshl_add_u32 v226, v226, 2, 0
	v_add_u32_e32 v226, 0x11000, v226
	ds_read_b32 v226, v226
	v_add_u32_e32 v227, s15, v245
	v_lshl_add_u32 v227, v227, 2, 0
	v_add_u32_e32 v227, 0x11000, v227
	ds_read_b32 v227, v227
	s_waitcnt lgkmcnt(7)
	v_add_f32_e32 v210, v74, v210
	v_cndmask_b32_e64 v85, v85, v210, s[6:7]
	s_waitcnt lgkmcnt(6)
	v_add_f32_e32 v211, v75, v211
	v_cndmask_b32_e64 v84, v84, v211, s[22:23]
	v_mov_b32_e32 v74, 0xf149f2ca
	v_mov_b32_e32 v75, 0xf149f2ca
	s_waitcnt lgkmcnt(5)
	v_add_f32_e32 v212, v72, v212
	v_cndmask_b32_e64 v75, v75, v212, s[28:29]
	s_waitcnt lgkmcnt(4)
	v_add_f32_e32 v213, v73, v213
	v_cndmask_b32_e64 v74, v74, v213, s[30:31]
	v_pk_mul_f32 v[66:67], v[70:71], v[66:67]
	v_pk_mul_f32 v[64:65], v[68:69], v[64:65]
	v_mov_b32_e32 v68, 0xf149f2ca
	v_mov_b32_e32 v69, 0xf149f2ca
	s_waitcnt lgkmcnt(3)
	v_add_f32_e32 v224, v64, v224
	v_cndmask_b32_e64 v69, v69, v224, s[36:37]
	s_waitcnt lgkmcnt(2)
	v_add_f32_e32 v225, v65, v225
	v_cndmask_b32_e64 v68, v68, v225, s[38:39]
	v_mov_b32_e32 v64, 0xf149f2ca
	v_mov_b32_e32 v65, 0xf149f2ca
	s_waitcnt lgkmcnt(1)
	v_add_f32_e32 v226, v66, v226
	v_cndmask_b32_e64 v65, v65, v226, s[44:45]
	s_waitcnt lgkmcnt(0)
	v_add_f32_e32 v227, v67, v227
	v_cndmask_b32_e64 v64, v64, v227, s[0:1]
	s_branch .LBB0_184
